# GEMM K-loops: 8 s_nop 0 per iteration in the load segments absorbed by placing the address v_lshl_add_u64 between each m0 write and its LDS-DMA load
# baseline (speedup 1.0000x reference)
; #define PG8_STAGE(bufoff, gbase, voff) do { _Pragma("unroll") for (int _i = 0; _i < 2; ++_i) \
;         __builtin_amdgcn_global_load_lds((const unsigned*)((const char*)(gbase) + (voff)[_i]), (LAS unsigned*)(lds + (bufoff) + ldsw + _i * 8192), 16, 0, 0); } while (0)
; #define PG8_LDA(dst, b, h) do { _Pragma("unroll") for (int m = 0; m < 4; ++m) _Pragma("unroll") for (int k = 0; k < 2; ++k) dst[m][k] = *(const LAS bf16x8*)(lds + PG8_SA(b, h) + aoff + m * 2048 + k * 1024); } while (0)
; #define PG8_LDB(dst, b, h) do { _Pragma("unroll") for (int n = 0; n < 2; ++n) _Pragma("unroll") for (int k = 0; k < 2; ++k) dst[n][k] = *(const LAS bf16x8*)(lds + PG8_SB(b, h) + boff + n * 2048 + k * 1024); } while (0)
; #define PG8_MMA(ai, bj, At, Bt) do { __builtin_amdgcn_s_setprio(1); _Pragma("unroll") for (int m = 0; m < 4; ++m) _Pragma("unroll") for (int n = 0; n < 2; ++n) _Pragma("unroll") for (int k = 0; k < 2; ++k) \
;         acc[ai][bj][m][n] = __builtin_amdgcn_mfma_f32_16x16x32_bf16(Bt[n][k], At[m][k], acc[ai][bj][m][n], 0, 0, 0); __builtin_amdgcn_s_setprio(0); } while (0)
; #define PG8_WAIT_V(n) asm volatile("s_waitcnt vmcnt(" #n ")" ::: "memory")
; #define PG8_WAIT_L(n) asm volatile("s_waitcnt lgkmcnt(" #n ")" ::: "memory")
; #define PG8_BAR __builtin_amdgcn_s_barrier()
; template <class Epi, class Sched = StaticOrder, class EpiSub = NoSub, bool FAST = false>
; __device__ __forceinline__ void gemm_phase(LAS unsigned char* lds, const Gemm g, const Sched& S, const Epi& E, const EpiSub& ES = EpiSub()) {
;     ...
;             const bool last = (t == nt - 2);
;             const char* a1 = cA + (size_t)(t + 1) * kstep;
;             const char* a2 = last ? nA : cA + (size_t)(t + 2) * kstep; const char* b2 = last ? nB : cB + (size_t)(t + 2) * kstep;
;             const char* a3 = a2 + kstep; const char* b3 = b2 + kstep;
;             if constexpr (FAST && PG8_SP2) {
;             PG8_LDB(B0, 0, 0); PG8_LDB(B1, 0, 1); PG8_SCHED; PG8_LDA(At, 0, 0); PG8_STAGE(PG8_SA(1, 1), a1 + hstepA, voffA);
;             PG8_WAIT_V(8); PG8_WAIT_L(0); PG8_BAR; PG8_MMA(0, 0, At, B0); PG8_MMA(0, 1, At, B1); PG8_BAR; PG8_SCHED;
;             PG8_LDA(At, 0, 1); PG8_STAGE(PG8_SB(0, 0), b2, voffB); PG8_STAGE(PG8_SB(0, 1), b2 + hstepB, voffB); PG8_STAGE(PG8_SA(0, 0), a2, voffA);
;             PG8_WAIT_V(8); PG8_WAIT_L(0); PG8_BAR; PG8_MMA(1, 0, At, B0); PG8_MMA(1, 1, At, B1); PG8_BAR; PG8_SCHED;
.LBB0_216:
	ds_read_b128 v[154:157], v150
	ds_read_b128 v[158:161], v150 offset:1024
	ds_read_b128 v[162:165], v150 offset:2048
	ds_read_b128 v[166:169], v150 offset:3072
	ds_read_b128 v[170:173], v151
	ds_read_b128 v[174:177], v151 offset:1024
	ds_read_b128 v[178:181], v151 offset:2048
	ds_read_b128 v[182:185], v151 offset:3072
	s_add_u32 s24, s22, 0xfff80080
	s_addc_u32 s25, s23, -1
	s_cmp_eq_u32 s50, 28
	s_cselect_b32 s27, s2, s25
	s_cselect_b32 s26, s3, s24
	s_cselect_b32 s25, s13, s49
	s_cselect_b32 s24, s15, s48
	v_lshl_add_u64 v[144:145], s[22:23], 0, v[136:137]
	s_add_i32 m0, s21, 0xc000
	ds_read_b128 v[186:189], v152
	ds_read_b128 v[194:197], v152 offset:1024
	ds_read_b128 v[198:201], v152 offset:2048
	ds_read_b128 v[202:205], v152 offset:3072
	ds_read_b128 v[206:209], v152 offset:4096
	ds_read_b128 v[210:213], v152 offset:5120
	ds_read_b128 v[214:217], v152 offset:6144
	ds_read_b128 v[218:221], v152 offset:7168
	global_load_lds_dwordx4 v[144:145], off
	s_add_i32 m0, s21, 0xe000
	v_lshl_add_u64 v[144:145], s[22:23], 0, v[138:139]
	global_load_lds_dwordx4 v[144:145], off
	s_waitcnt vmcnt(8)
	s_waitcnt lgkmcnt(0)
	s_setprio 1
	s_barrier
	v_mfma_f32_16x16x32_bf16 v[124:127], v[154:157], v[186:189], v[124:127]
	v_mfma_f32_16x16x32_bf16 v[120:123], v[162:165], v[186:189], v[120:123]
	v_mfma_f32_16x16x32_bf16 v[116:119], v[154:157], v[198:201], v[116:119]
	v_mfma_f32_16x16x32_bf16 v[108:111], v[162:165], v[198:201], v[108:111]
	v_mfma_f32_16x16x32_bf16 v[100:103], v[154:157], v[206:209], v[100:103]
	v_mfma_f32_16x16x32_bf16 v[92:95], v[162:165], v[206:209], v[92:95]
	v_mfma_f32_16x16x32_bf16 v[84:87], v[154:157], v[214:217], v[84:87]
	v_mfma_f32_16x16x32_bf16 v[76:79], v[162:165], v[214:217], v[76:79]
	v_mfma_f32_16x16x32_bf16 v[124:127], v[158:161], v[194:197], v[124:127]
	v_mfma_f32_16x16x32_bf16 v[120:123], v[166:169], v[194:197], v[120:123]
	v_mfma_f32_16x16x32_bf16 v[116:119], v[158:161], v[202:205], v[116:119]
	v_mfma_f32_16x16x32_bf16 v[108:111], v[166:169], v[202:205], v[108:111]
	v_mfma_f32_16x16x32_bf16 v[100:103], v[158:161], v[210:213], v[100:103]
	v_mfma_f32_16x16x32_bf16 v[92:95], v[166:169], v[210:213], v[92:95]
	v_mfma_f32_16x16x32_bf16 v[84:87], v[158:161], v[218:221], v[84:87]
	v_mfma_f32_16x16x32_bf16 v[76:79], v[166:169], v[218:221], v[76:79]
	v_mfma_f32_16x16x32_bf16 v[112:115], v[170:173], v[186:189], v[112:115]
	v_mfma_f32_16x16x32_bf16 v[104:107], v[178:181], v[186:189], v[104:107]
	v_mfma_f32_16x16x32_bf16 v[96:99], v[170:173], v[198:201], v[96:99]
	v_mfma_f32_16x16x32_bf16 v[88:91], v[178:181], v[198:201], v[88:91]
	v_mfma_f32_16x16x32_bf16 v[80:83], v[170:173], v[206:209], v[80:83]
	v_mfma_f32_16x16x32_bf16 v[72:75], v[178:181], v[206:209], v[72:75]
	v_mfma_f32_16x16x32_bf16 v[68:71], v[170:173], v[214:217], v[68:71]
	v_mfma_f32_16x16x32_bf16 v[64:67], v[178:181], v[214:217], v[64:67]
	v_mfma_f32_16x16x32_bf16 v[112:115], v[174:177], v[194:197], v[112:115]
	v_mfma_f32_16x16x32_bf16 v[104:107], v[182:185], v[194:197], v[104:107]
	v_mfma_f32_16x16x32_bf16 v[96:99], v[174:177], v[202:205], v[96:99]
	v_mfma_f32_16x16x32_bf16 v[88:91], v[182:185], v[202:205], v[88:91]
	v_mfma_f32_16x16x32_bf16 v[80:83], v[174:177], v[210:213], v[80:83]
	v_mfma_f32_16x16x32_bf16 v[72:75], v[182:185], v[210:213], v[72:75]
	v_mfma_f32_16x16x32_bf16 v[68:71], v[174:177], v[218:221], v[68:71]
	v_mfma_f32_16x16x32_bf16 v[64:67], v[182:185], v[218:221], v[64:67]
	s_barrier
	s_setprio 0
	s_add_i32 s51, s41, s30
	v_lshl_add_u64 v[144:145], s[24:25], 0, v[130:131]
	s_mov_b32 m0, s51
	ds_read_b128 v[186:189], v152 offset:16384
	ds_read_b128 v[194:197], v152 offset:17408
	ds_read_b128 v[198:201], v152 offset:18432
	ds_read_b128 v[202:205], v152 offset:19456
	ds_read_b128 v[206:209], v152 offset:20480
	ds_read_b128 v[210:213], v152 offset:21504
	ds_read_b128 v[214:217], v152 offset:22528
	ds_read_b128 v[218:221], v152 offset:23552
	global_load_lds_dwordx4 v[144:145], off
	s_add_i32 m0, s51, 0x2000
	s_add_u32 s68, s24, 0x80000
	v_lshl_add_u64 v[190:191], s[24:25], 0, v[134:135]
	s_addc_u32 s69, s25, 0
	s_add_i32 s51, s42, s30
	global_load_lds_dwordx4 v[190:191], off
	v_lshl_add_u64 v[222:223], s[68:69], 0, v[130:131]
	s_mov_b32 m0, s51
	v_lshl_add_u64 v[224:225], s[26:27], 0, v[132:133]
	global_load_lds_dwordx4 v[222:223], off
	s_add_i32 m0, s51, 0x2000
	v_lshl_add_u64 v[222:223], s[68:69], 0, v[134:135]
	global_load_lds_dwordx4 v[222:223], off
	s_mov_b32 m0, s21
	v_lshl_add_u64 v[222:223], s[26:27], 0, v[128:129]
	global_load_lds_dwordx4 v[222:223], off
	s_mov_b32 m0, s34
	s_nop 0
	global_load_lds_dwordx4 v[224:225], off
	s_waitcnt vmcnt(8)
	s_waitcnt lgkmcnt(0)
	s_setprio 1
	s_barrier
; #define PG8_STAGE(bufoff, gbase, voff) do { _Pragma("unroll") for (int _i = 0; _i < 2; ++_i) \
;         __builtin_amdgcn_global_load_lds((const unsigned*)((const char*)(gbase) + (voff)[_i]), (LAS unsigned*)(lds + (bufoff) + ldsw + _i * 8192), 16, 0, 0); } while (0)
; #define PG8_LDA(dst, b, h) do { _Pragma("unroll") for (int m = 0; m < 4; ++m) _Pragma("unroll") for (int k = 0; k < 2; ++k) dst[m][k] = *(const LAS bf16x8*)(lds + PG8_SA(b, h) + aoff + m * 2048 + k * 1024); } while (0)
; #define PG8_LDB(dst, b, h) do { _Pragma("unroll") for (int n = 0; n < 2; ++n) _Pragma("unroll") for (int k = 0; k < 2; ++k) dst[n][k] = *(const LAS bf16x8*)(lds + PG8_SB(b, h) + boff + n * 2048 + k * 1024); } while (0)
; #define PG8_MMA(ai, bj, At, Bt) do { __builtin_amdgcn_s_setprio(1); _Pragma("unroll") for (int m = 0; m < 4; ++m) _Pragma("unroll") for (int n = 0; n < 2; ++n) _Pragma("unroll") for (int k = 0; k < 2; ++k) \
;         acc[ai][bj][m][n] = __builtin_amdgcn_mfma_f32_16x16x32_bf16(Bt[n][k], At[m][k], acc[ai][bj][m][n], 0, 0, 0); __builtin_amdgcn_s_setprio(0); } while (0)
; #define PG8_WAIT_V(n) asm volatile("s_waitcnt vmcnt(" #n ")" ::: "memory")
; #define PG8_WAIT_L(n) asm volatile("s_waitcnt lgkmcnt(" #n ")" ::: "memory")
; #define PG8_BAR __builtin_amdgcn_s_barrier()
; #define PG8_SCHED __builtin_amdgcn_sched_barrier(0)
; template <class Epi, class Sched = StaticOrder, class EpiSub = NoSub, bool FAST = false>
; __device__ __forceinline__ void gemm_phase(LAS unsigned char* lds, const Gemm g, const Sched& S, const Epi& E, const EpiSub& ES = EpiSub()) {
;     ...
;             PG8_WAIT_V(8); PG8_WAIT_L(0); PG8_BAR; PG8_MMA(1, 0, At, B0); PG8_MMA(1, 1, At, B1); PG8_BAR; PG8_SCHED;
;             PG8_LDB(B0, 1, 0); PG8_LDB(B1, 1, 1); PG8_SCHED; PG8_LDA(At, 1, 0); PG8_STAGE(PG8_SA(0, 1), a2 + hstepA, voffA);
;             PG8_WAIT_V(8); PG8_WAIT_L(0); PG8_BAR; PG8_MMA(0, 0, At, B0); PG8_MMA(0, 1, At, B1); PG8_BAR; PG8_SCHED;
	v_mfma_f32_16x16x32_bf16 v[60:63], v[154:157], v[186:189], v[60:63]
	v_mfma_f32_16x16x32_bf16 v[56:59], v[162:165], v[186:189], v[56:59]
	v_mfma_f32_16x16x32_bf16 v[52:55], v[154:157], v[198:201], v[52:55]
	v_mfma_f32_16x16x32_bf16 v[44:47], v[162:165], v[198:201], v[44:47]
	v_mfma_f32_16x16x32_bf16 v[36:39], v[154:157], v[206:209], v[36:39]
	v_mfma_f32_16x16x32_bf16 v[28:31], v[162:165], v[206:209], v[28:31]
	v_mfma_f32_16x16x32_bf16 v[20:23], v[154:157], v[214:217], v[20:23]
	v_mfma_f32_16x16x32_bf16 v[12:15], v[162:165], v[214:217], v[12:15]
	v_mfma_f32_16x16x32_bf16 v[60:63], v[158:161], v[194:197], v[60:63]
	v_mfma_f32_16x16x32_bf16 v[56:59], v[166:169], v[194:197], v[56:59]
	v_mfma_f32_16x16x32_bf16 v[52:55], v[158:161], v[202:205], v[52:55]
	v_mfma_f32_16x16x32_bf16 v[44:47], v[166:169], v[202:205], v[44:47]
	v_mfma_f32_16x16x32_bf16 v[36:39], v[158:161], v[210:213], v[36:39]
	v_mfma_f32_16x16x32_bf16 v[28:31], v[166:169], v[210:213], v[28:31]
	v_mfma_f32_16x16x32_bf16 v[20:23], v[158:161], v[218:221], v[20:23]
	v_mfma_f32_16x16x32_bf16 v[12:15], v[166:169], v[218:221], v[12:15]
	v_mfma_f32_16x16x32_bf16 v[48:51], v[170:173], v[186:189], v[48:51]
	v_mfma_f32_16x16x32_bf16 v[40:43], v[178:181], v[186:189], v[40:43]
	v_mfma_f32_16x16x32_bf16 v[32:35], v[170:173], v[198:201], v[32:35]
	v_mfma_f32_16x16x32_bf16 v[24:27], v[178:181], v[198:201], v[24:27]
	v_mfma_f32_16x16x32_bf16 v[16:19], v[170:173], v[206:209], v[16:19]
	v_mfma_f32_16x16x32_bf16 v[8:11], v[178:181], v[206:209], v[8:11]
	v_mfma_f32_16x16x32_bf16 v[4:7], v[170:173], v[214:217], v[4:7]
	v_mfma_f32_16x16x32_bf16 v[0:3], v[178:181], v[214:217], v[0:3]
	v_mfma_f32_16x16x32_bf16 v[48:51], v[174:177], v[194:197], v[48:51]
	v_mfma_f32_16x16x32_bf16 v[40:43], v[182:185], v[194:197], v[40:43]
	v_mfma_f32_16x16x32_bf16 v[32:35], v[174:177], v[202:205], v[32:35]
	v_mfma_f32_16x16x32_bf16 v[24:27], v[182:185], v[202:205], v[24:27]
	v_mfma_f32_16x16x32_bf16 v[16:19], v[174:177], v[210:213], v[16:19]
	v_mfma_f32_16x16x32_bf16 v[8:11], v[182:185], v[210:213], v[8:11]
	v_mfma_f32_16x16x32_bf16 v[4:7], v[174:177], v[218:221], v[4:7]
	v_mfma_f32_16x16x32_bf16 v[0:3], v[182:185], v[218:221], v[0:3]
	s_barrier
	s_setprio 0
	s_add_i32 s51, 0, 0x18000
	v_add_u32_e32 v153, s51, v148
	s_add_i32 s68, 0, 0x1c000
	ds_read_b128 v[154:157], v153
	ds_read_b128 v[158:161], v153 offset:1024
	ds_read_b128 v[162:165], v153 offset:2048
	ds_read_b128 v[166:169], v153 offset:3072
	v_add_u32_e32 v153, s68, v148
	ds_read_b128 v[170:173], v153
	ds_read_b128 v[174:177], v153 offset:1024
	ds_read_b128 v[178:181], v153 offset:2048
	ds_read_b128 v[182:185], v153 offset:3072
	s_add_u32 s26, s26, 0x80000
	s_addc_u32 s27, s27, 0
	s_mov_b32 m0, s35
	v_lshl_add_u64 v[226:227], s[26:27], 0, v[128:129]
	ds_read_b128 v[186:189], v152 offset:32768
	ds_read_b128 v[194:197], v152 offset:33792
	ds_read_b128 v[198:201], v152 offset:34816
	ds_read_b128 v[202:205], v152 offset:35840
	ds_read_b128 v[206:209], v152 offset:36864
	ds_read_b128 v[210:213], v152 offset:37888
	ds_read_b128 v[214:217], v152 offset:38912
	ds_read_b128 v[218:221], v152 offset:39936
	global_load_lds_dwordx4 v[226:227], off
	s_mov_b32 m0, s36
	v_lshl_add_u64 v[226:227], s[26:27], 0, v[132:133]
	global_load_lds_dwordx4 v[226:227], off
	s_waitcnt vmcnt(8)
	s_waitcnt lgkmcnt(0)
	s_setprio 1
	s_barrier
	v_mfma_f32_16x16x32_bf16 v[124:127], v[154:157], v[186:189], v[124:127]
	v_mfma_f32_16x16x32_bf16 v[120:123], v[162:165], v[186:189], v[120:123]
	v_mfma_f32_16x16x32_bf16 v[116:119], v[154:157], v[198:201], v[116:119]
	v_mfma_f32_16x16x32_bf16 v[108:111], v[162:165], v[198:201], v[108:111]
	v_mfma_f32_16x16x32_bf16 v[100:103], v[154:157], v[206:209], v[100:103]
	v_mfma_f32_16x16x32_bf16 v[92:95], v[162:165], v[206:209], v[92:95]
	v_mfma_f32_16x16x32_bf16 v[84:87], v[154:157], v[214:217], v[84:87]
	v_mfma_f32_16x16x32_bf16 v[76:79], v[162:165], v[214:217], v[76:79]
	v_mfma_f32_16x16x32_bf16 v[124:127], v[158:161], v[194:197], v[124:127]
	v_mfma_f32_16x16x32_bf16 v[120:123], v[166:169], v[194:197], v[120:123]
	v_mfma_f32_16x16x32_bf16 v[116:119], v[158:161], v[202:205], v[116:119]
	v_mfma_f32_16x16x32_bf16 v[108:111], v[166:169], v[202:205], v[108:111]
	v_mfma_f32_16x16x32_bf16 v[100:103], v[158:161], v[210:213], v[100:103]
	v_mfma_f32_16x16x32_bf16 v[92:95], v[166:169], v[210:213], v[92:95]
	v_mfma_f32_16x16x32_bf16 v[84:87], v[158:161], v[218:221], v[84:87]
	v_mfma_f32_16x16x32_bf16 v[76:79], v[166:169], v[218:221], v[76:79]
	v_mfma_f32_16x16x32_bf16 v[112:115], v[170:173], v[186:189], v[112:115]
	v_mfma_f32_16x16x32_bf16 v[104:107], v[178:181], v[186:189], v[104:107]
	v_mfma_f32_16x16x32_bf16 v[96:99], v[170:173], v[198:201], v[96:99]
	v_mfma_f32_16x16x32_bf16 v[88:91], v[178:181], v[198:201], v[88:91]
	v_mfma_f32_16x16x32_bf16 v[80:83], v[170:173], v[206:209], v[80:83]
	v_mfma_f32_16x16x32_bf16 v[72:75], v[178:181], v[206:209], v[72:75]
	v_mfma_f32_16x16x32_bf16 v[68:71], v[170:173], v[214:217], v[68:71]
	v_mfma_f32_16x16x32_bf16 v[64:67], v[178:181], v[214:217], v[64:67]
	v_mfma_f32_16x16x32_bf16 v[112:115], v[174:177], v[194:197], v[112:115]
	v_mfma_f32_16x16x32_bf16 v[104:107], v[182:185], v[194:197], v[104:107]
	v_mfma_f32_16x16x32_bf16 v[96:99], v[174:177], v[202:205], v[96:99]
	v_mfma_f32_16x16x32_bf16 v[88:91], v[182:185], v[202:205], v[88:91]
	v_mfma_f32_16x16x32_bf16 v[80:83], v[174:177], v[210:213], v[80:83]
	v_mfma_f32_16x16x32_bf16 v[72:75], v[182:185], v[210:213], v[72:75]
	v_mfma_f32_16x16x32_bf16 v[68:71], v[174:177], v[218:221], v[68:71]
	v_mfma_f32_16x16x32_bf16 v[64:67], v[182:185], v[218:221], v[64:67]
	s_barrier
; #define PG8_STAGE(bufoff, gbase, voff) do { _Pragma("unroll") for (int _i = 0; _i < 2; ++_i) \
;         __builtin_amdgcn_global_load_lds((const unsigned*)((const char*)(gbase) + (voff)[_i]), (LAS unsigned*)(lds + (bufoff) + ldsw + _i * 8192), 16, 0, 0); } while (0)
; #define PG8_LDA(dst, b, h) do { _Pragma("unroll") for (int m = 0; m < 4; ++m) _Pragma("unroll") for (int k = 0; k < 2; ++k) dst[m][k] = *(const LAS bf16x8*)(lds + PG8_SA(b, h) + aoff + m * 2048 + k * 1024); } while (0)
; #define PG8_MMA(ai, bj, At, Bt) do { __builtin_amdgcn_s_setprio(1); _Pragma("unroll") for (int m = 0; m < 4; ++m) _Pragma("unroll") for (int n = 0; n < 2; ++n) _Pragma("unroll") for (int k = 0; k < 2; ++k) \
;         acc[ai][bj][m][n] = __builtin_amdgcn_mfma_f32_16x16x32_bf16(Bt[n][k], At[m][k], acc[ai][bj][m][n], 0, 0, 0); __builtin_amdgcn_s_setprio(0); } while (0)
; #define PG8_WAIT_V(n) asm volatile("s_waitcnt vmcnt(" #n ")" ::: "memory")
; #define PG8_WAIT_L(n) asm volatile("s_waitcnt lgkmcnt(" #n ")" ::: "memory")
; #define PG8_BAR __builtin_amdgcn_s_barrier()
; #define PG8_SCHED __builtin_amdgcn_sched_barrier(0)
; template <class Epi, class Sched = StaticOrder, class EpiSub = NoSub, bool FAST = false>
; __device__ __forceinline__ void gemm_phase(LAS unsigned char* lds, const Gemm g, const Sched& S, const Epi& E, const EpiSub& ES = EpiSub()) {
;     ...
;             PG8_LDA(At, 1, 1); PG8_STAGE(PG8_SB(1, 0), b3, voffB); PG8_STAGE(PG8_SB(1, 1), b3 + hstepB, voffB); PG8_STAGE(PG8_SA(1, 0), a3, voffA);
;             PG8_WAIT_V(8); PG8_WAIT_L(0); PG8_BAR; PG8_MMA(1, 0, At, B0); PG8_MMA(1, 1, At, B1); PG8_BAR; PG8_SCHED;
;     ...
;         if constexpr (FAST && PG8_ALIGN) { if (wr == 0) PG8_BAR; }
	s_setprio 0
	s_add_i32 s26, s51, s30
	v_lshl_add_u64 v[144:145], v[144:145], 0, s[8:9]
	s_mov_b32 m0, s26
	ds_read_b128 v[186:189], v152 offset:49152
	ds_read_b128 v[194:197], v152 offset:50176
	ds_read_b128 v[198:201], v152 offset:51200
	ds_read_b128 v[202:205], v152 offset:52224
	ds_read_b128 v[206:209], v152 offset:53248
	ds_read_b128 v[210:213], v152 offset:54272
	ds_read_b128 v[214:217], v152 offset:55296
	ds_read_b128 v[218:221], v152 offset:56320
	global_load_lds_dwordx4 v[144:145], off
	s_add_i32 m0, s26, 0x2000
	s_add_u32 s24, s24, 0x80080
	v_lshl_add_u64 v[144:145], v[190:191], 0, s[8:9]
	s_addc_u32 s25, s25, 0
	s_add_i32 s26, s68, s30
	global_load_lds_dwordx4 v[144:145], off
	s_mov_b32 m0, s26
	v_lshl_add_u64 v[144:145], s[24:25], 0, v[130:131]
	global_load_lds_dwordx4 v[144:145], off
	s_add_i32 m0, s26, 0x2000
	v_lshl_add_u64 v[144:145], s[24:25], 0, v[134:135]
	global_load_lds_dwordx4 v[144:145], off
	s_mov_b32 m0, s39
	v_lshl_add_u64 v[144:145], v[222:223], 0, s[8:9]
	global_load_lds_dwordx4 v[144:145], off
	s_mov_b32 m0, s40
	v_lshl_add_u64 v[144:145], v[224:225], 0, s[8:9]
	global_load_lds_dwordx4 v[144:145], off
	s_waitcnt vmcnt(8)
	s_waitcnt lgkmcnt(0)
	s_setprio 1
	s_barrier
	v_mfma_f32_16x16x32_bf16 v[60:63], v[154:157], v[186:189], v[60:63]
	v_mfma_f32_16x16x32_bf16 v[56:59], v[162:165], v[186:189], v[56:59]
	v_mfma_f32_16x16x32_bf16 v[52:55], v[154:157], v[198:201], v[52:55]
	v_mfma_f32_16x16x32_bf16 v[44:47], v[162:165], v[198:201], v[44:47]
	v_mfma_f32_16x16x32_bf16 v[36:39], v[154:157], v[206:209], v[36:39]
	v_mfma_f32_16x16x32_bf16 v[28:31], v[162:165], v[206:209], v[28:31]
	v_mfma_f32_16x16x32_bf16 v[20:23], v[154:157], v[214:217], v[20:23]
	v_mfma_f32_16x16x32_bf16 v[12:15], v[162:165], v[214:217], v[12:15]
	v_mfma_f32_16x16x32_bf16 v[60:63], v[158:161], v[194:197], v[60:63]
	v_mfma_f32_16x16x32_bf16 v[56:59], v[166:169], v[194:197], v[56:59]
	v_mfma_f32_16x16x32_bf16 v[52:55], v[158:161], v[202:205], v[52:55]
	v_mfma_f32_16x16x32_bf16 v[44:47], v[166:169], v[202:205], v[44:47]
	v_mfma_f32_16x16x32_bf16 v[36:39], v[158:161], v[210:213], v[36:39]
	v_mfma_f32_16x16x32_bf16 v[28:31], v[166:169], v[210:213], v[28:31]
	v_mfma_f32_16x16x32_bf16 v[20:23], v[158:161], v[218:221], v[20:23]
	v_mfma_f32_16x16x32_bf16 v[12:15], v[166:169], v[218:221], v[12:15]
	v_mfma_f32_16x16x32_bf16 v[48:51], v[170:173], v[186:189], v[48:51]
	v_mfma_f32_16x16x32_bf16 v[40:43], v[178:181], v[186:189], v[40:43]
	v_mfma_f32_16x16x32_bf16 v[32:35], v[170:173], v[198:201], v[32:35]
	v_mfma_f32_16x16x32_bf16 v[24:27], v[178:181], v[198:201], v[24:27]
	v_mfma_f32_16x16x32_bf16 v[16:19], v[170:173], v[206:209], v[16:19]
	v_mfma_f32_16x16x32_bf16 v[8:11], v[178:181], v[206:209], v[8:11]
	v_mfma_f32_16x16x32_bf16 v[4:7], v[170:173], v[214:217], v[4:7]
	v_mfma_f32_16x16x32_bf16 v[0:3], v[178:181], v[214:217], v[0:3]
	v_mfma_f32_16x16x32_bf16 v[48:51], v[174:177], v[194:197], v[48:51]
	v_mfma_f32_16x16x32_bf16 v[40:43], v[182:185], v[194:197], v[40:43]
	v_mfma_f32_16x16x32_bf16 v[32:35], v[174:177], v[202:205], v[32:35]
	v_mfma_f32_16x16x32_bf16 v[24:27], v[182:185], v[202:205], v[24:27]
	v_mfma_f32_16x16x32_bf16 v[16:19], v[174:177], v[210:213], v[16:19]
	v_mfma_f32_16x16x32_bf16 v[8:11], v[182:185], v[210:213], v[8:11]
	v_mfma_f32_16x16x32_bf16 v[4:7], v[174:177], v[218:221], v[4:7]
	v_mfma_f32_16x16x32_bf16 v[0:3], v[182:185], v[218:221], v[0:3]
	s_barrier
	s_setprio 0
	s_add_i32 s50, s50, 2
	s_add_u32 s22, s22, 0x100
	s_addc_u32 s23, s23, 0
	s_add_u32 s48, s48, 0x100
	s_addc_u32 s49, s49, 0
	s_cmp_gt_u32 s50, 29
	s_cbranch_scc0 .LBB0_216
	s_and_b64 vcc, exec, s[10:11]
	s_cbranch_vccz .LBB0_219
	s_barrier

; #define PG8_STAGE(bufoff, gbase, voff) do { _Pragma("unroll") for (int _i = 0; _i < 2; ++_i) \
;         __builtin_amdgcn_global_load_lds((const unsigned*)((const char*)(gbase) + (voff)[_i]), (LAS unsigned*)(lds + (bufoff) + ldsw + _i * 8192), 16, 0, 0); } while (0)
; #define PG8_LDA(dst, b, h) do { _Pragma("unroll") for (int m = 0; m < 4; ++m) _Pragma("unroll") for (int k = 0; k < 2; ++k) dst[m][k] = *(const LAS bf16x8*)(lds + PG8_SA(b, h) + aoff + m * 2048 + k * 1024); } while (0)
; #define PG8_LDB(dst, b, h) do { _Pragma("unroll") for (int n = 0; n < 2; ++n) _Pragma("unroll") for (int k = 0; k < 2; ++k) dst[n][k] = *(const LAS bf16x8*)(lds + PG8_SB(b, h) + boff + n * 2048 + k * 1024); } while (0)
; #define PG8_MMA(ai, bj, At, Bt) do { __builtin_amdgcn_s_setprio(1); _Pragma("unroll") for (int m = 0; m < 4; ++m) _Pragma("unroll") for (int n = 0; n < 2; ++n) _Pragma("unroll") for (int k = 0; k < 2; ++k) \
;         acc[ai][bj][m][n] = __builtin_amdgcn_mfma_f32_16x16x32_bf16(Bt[n][k], At[m][k], acc[ai][bj][m][n], 0, 0, 0); __builtin_amdgcn_s_setprio(0); } while (0)
; #define PG8_WAIT_V(n) asm volatile("s_waitcnt vmcnt(" #n ")" ::: "memory")
; #define PG8_WAIT_L(n) asm volatile("s_waitcnt lgkmcnt(" #n ")" ::: "memory")
; #define PG8_BAR __builtin_amdgcn_s_barrier()
; #define PG8_SCHED __builtin_amdgcn_sched_barrier(0)
; template <class Epi, class Sched = StaticOrder, class EpiSub = NoSub, bool FAST = false>
; __device__ __forceinline__ void gemm_phase(LAS unsigned char* lds, const Gemm g, const Sched& S, const Epi& E, const EpiSub& ES = EpiSub()) {
;     ...
;         for (int t = 0; t < nt; t += 2) {
;             const bool last = (t == nt - 2);
;             const char* a1 = cA + (size_t)(t + 1) * kstep;
;             const char* a2 = last ? nA : cA + (size_t)(t + 2) * kstep; const char* b2 = last ? nB : cB + (size_t)(t + 2) * kstep;
;             const char* a3 = a2 + kstep; const char* b3 = b2 + kstep;
;             if constexpr (FAST && PG8_SP2) {
;             PG8_LDB(B0, 0, 0); PG8_LDB(B1, 0, 1); PG8_SCHED; PG8_LDA(At, 0, 0); PG8_STAGE(PG8_SA(1, 1), a1 + hstepA, voffA);
;             PG8_WAIT_V(8); PG8_WAIT_L(0); PG8_BAR; PG8_MMA(0, 0, At, B0); PG8_MMA(0, 1, At, B1); PG8_BAR; PG8_SCHED;
;             PG8_LDA(At, 0, 1); PG8_STAGE(PG8_SB(0, 0), b2, voffB); PG8_STAGE(PG8_SB(0, 1), b2 + hstepB, voffB); PG8_STAGE(PG8_SA(0, 0), a2, voffA);
.LBB0_600:
	ds_read_b128 v[100:103], v186
	ds_read_b128 v[112:115], v186 offset:1024
	ds_read_b128 v[124:127], v186 offset:2048
	ds_read_b128 v[136:139], v186 offset:3072
	ds_read_b128 v[144:147], v187
	ds_read_b128 v[148:151], v187 offset:1024
	ds_read_b128 v[152:155], v187 offset:2048
	ds_read_b128 v[170:173], v187 offset:3072
	s_add_i32 s51, s50, 2
	s_add_u32 s42, s40, 0xfffc0080
	s_addc_u32 s43, s41, -1
	s_cmp_eq_u32 s33, s50
	s_cselect_b32 s53, s1, s43
	s_cselect_b32 s52, s5, s42
	s_cselect_b32 s43, s7, s49
	s_cselect_b32 s42, s25, s48
	v_lshl_add_u64 v[190:191], s[40:41], 0, v[164:165]
	s_add_i32 m0, s55, 0xc000
	ds_read_b128 v[174:177], v188
	ds_read_b128 v[178:181], v188 offset:1024
	ds_read_b128 v[194:197], v188 offset:2048
	ds_read_b128 v[198:201], v188 offset:3072
	ds_read_b128 v[202:205], v188 offset:4096
	ds_read_b128 v[206:209], v188 offset:5120
	ds_read_b128 v[210:213], v188 offset:6144
	ds_read_b128 v[214:217], v188 offset:7168
	global_load_lds_dwordx4 v[190:191], off
	s_add_i32 m0, s55, 0xe000
	v_lshl_add_u64 v[190:191], s[40:41], 0, v[166:167]
	global_load_lds_dwordx4 v[190:191], off
	s_waitcnt vmcnt(8)
	s_waitcnt lgkmcnt(0)
	s_setprio 1
	s_barrier
	v_mfma_f32_16x16x32_bf16 v[140:143], v[100:103], v[174:177], v[140:143]
	v_mfma_f32_16x16x32_bf16 v[132:135], v[124:127], v[174:177], v[132:135]
	v_mfma_f32_16x16x32_bf16 v[116:119], v[100:103], v[194:197], v[116:119]
	v_mfma_f32_16x16x32_bf16 v[108:111], v[124:127], v[194:197], v[108:111]
	v_mfma_f32_16x16x32_bf16 v[92:95], v[100:103], v[202:205], v[92:95]
	v_mfma_f32_16x16x32_bf16 v[88:91], v[124:127], v[202:205], v[88:91]
	v_mfma_f32_16x16x32_bf16 v[76:79], v[100:103], v[210:213], v[76:79]
	v_mfma_f32_16x16x32_bf16 v[72:75], v[124:127], v[210:213], v[72:75]
	v_mfma_f32_16x16x32_bf16 v[140:143], v[112:115], v[178:181], v[140:143]
	v_mfma_f32_16x16x32_bf16 v[132:135], v[136:139], v[178:181], v[132:135]
	v_mfma_f32_16x16x32_bf16 v[116:119], v[112:115], v[198:201], v[116:119]
	v_mfma_f32_16x16x32_bf16 v[108:111], v[136:139], v[198:201], v[108:111]
	v_mfma_f32_16x16x32_bf16 v[92:95], v[112:115], v[206:209], v[92:95]
	v_mfma_f32_16x16x32_bf16 v[88:91], v[136:139], v[206:209], v[88:91]
	v_mfma_f32_16x16x32_bf16 v[76:79], v[112:115], v[214:217], v[76:79]
	v_mfma_f32_16x16x32_bf16 v[72:75], v[136:139], v[214:217], v[72:75]
	v_mfma_f32_16x16x32_bf16 v[128:131], v[144:147], v[174:177], v[128:131]
	v_mfma_f32_16x16x32_bf16 v[120:123], v[152:155], v[174:177], v[120:123]
	v_mfma_f32_16x16x32_bf16 v[104:107], v[144:147], v[194:197], v[104:107]
	v_mfma_f32_16x16x32_bf16 v[96:99], v[152:155], v[194:197], v[96:99]
	v_mfma_f32_16x16x32_bf16 v[84:87], v[144:147], v[202:205], v[84:87]
	v_mfma_f32_16x16x32_bf16 v[80:83], v[152:155], v[202:205], v[80:83]
	v_mfma_f32_16x16x32_bf16 v[68:71], v[144:147], v[210:213], v[68:71]
	v_mfma_f32_16x16x32_bf16 v[64:67], v[152:155], v[210:213], v[64:67]
	v_mfma_f32_16x16x32_bf16 v[128:131], v[148:151], v[178:181], v[128:131]
	v_mfma_f32_16x16x32_bf16 v[120:123], v[170:173], v[178:181], v[120:123]
	v_mfma_f32_16x16x32_bf16 v[104:107], v[148:151], v[198:201], v[104:107]
	v_mfma_f32_16x16x32_bf16 v[96:99], v[170:173], v[198:201], v[96:99]
	v_mfma_f32_16x16x32_bf16 v[84:87], v[148:151], v[206:209], v[84:87]
	v_mfma_f32_16x16x32_bf16 v[80:83], v[170:173], v[206:209], v[80:83]
	v_mfma_f32_16x16x32_bf16 v[68:71], v[148:151], v[214:217], v[68:71]
	v_mfma_f32_16x16x32_bf16 v[64:67], v[170:173], v[214:217], v[64:67]
	s_barrier
	s_setprio 0
	s_add_i32 s50, s75, s54
	v_lshl_add_u64 v[190:191], s[42:43], 0, v[158:159]
	s_mov_b32 m0, s50
	ds_read_b128 v[174:177], v188 offset:16384
	ds_read_b128 v[178:181], v188 offset:17408
	ds_read_b128 v[194:197], v188 offset:18432
	ds_read_b128 v[198:201], v188 offset:19456
	ds_read_b128 v[202:205], v188 offset:20480
	ds_read_b128 v[206:209], v188 offset:21504
	ds_read_b128 v[210:213], v188 offset:22528
	ds_read_b128 v[214:217], v188 offset:23552
	global_load_lds_dwordx4 v[190:191], off
	s_add_i32 m0, s50, 0x2000
	s_add_u32 s70, s42, 0x40000
	v_lshl_add_u64 v[218:219], s[42:43], 0, v[162:163]
	s_addc_u32 s71, s43, 0
	s_add_i32 s50, s80, s54
	global_load_lds_dwordx4 v[218:219], off
	v_lshl_add_u64 v[220:221], s[70:71], 0, v[158:159]
	s_mov_b32 m0, s50
	v_lshl_add_u64 v[222:223], s[52:53], 0, v[160:161]
	global_load_lds_dwordx4 v[220:221], off
	s_add_i32 m0, s50, 0x2000
	v_lshl_add_u64 v[220:221], s[70:71], 0, v[162:163]
	global_load_lds_dwordx4 v[220:221], off
	s_mov_b32 m0, s55
	v_lshl_add_u64 v[220:221], s[52:53], 0, v[156:157]
	global_load_lds_dwordx4 v[220:221], off
	s_mov_b32 m0, s56
	s_nop 0
	global_load_lds_dwordx4 v[222:223], off
	s_waitcnt vmcnt(8)
	s_waitcnt lgkmcnt(0)
	s_setprio 1
	s_barrier
; #define PG8_STAGE(bufoff, gbase, voff) do { _Pragma("unroll") for (int _i = 0; _i < 2; ++_i) \
;         __builtin_amdgcn_global_load_lds((const unsigned*)((const char*)(gbase) + (voff)[_i]), (LAS unsigned*)(lds + (bufoff) + ldsw + _i * 8192), 16, 0, 0); } while (0)
; #define PG8_LDA(dst, b, h) do { _Pragma("unroll") for (int m = 0; m < 4; ++m) _Pragma("unroll") for (int k = 0; k < 2; ++k) dst[m][k] = *(const LAS bf16x8*)(lds + PG8_SA(b, h) + aoff + m * 2048 + k * 1024); } while (0)
; #define PG8_LDB(dst, b, h) do { _Pragma("unroll") for (int n = 0; n < 2; ++n) _Pragma("unroll") for (int k = 0; k < 2; ++k) dst[n][k] = *(const LAS bf16x8*)(lds + PG8_SB(b, h) + boff + n * 2048 + k * 1024); } while (0)
; #define PG8_MMA(ai, bj, At, Bt) do { __builtin_amdgcn_s_setprio(1); _Pragma("unroll") for (int m = 0; m < 4; ++m) _Pragma("unroll") for (int n = 0; n < 2; ++n) _Pragma("unroll") for (int k = 0; k < 2; ++k) \
;         acc[ai][bj][m][n] = __builtin_amdgcn_mfma_f32_16x16x32_bf16(Bt[n][k], At[m][k], acc[ai][bj][m][n], 0, 0, 0); __builtin_amdgcn_s_setprio(0); } while (0)
; #define PG8_WAIT_V(n) asm volatile("s_waitcnt vmcnt(" #n ")" ::: "memory")
; #define PG8_WAIT_L(n) asm volatile("s_waitcnt lgkmcnt(" #n ")" ::: "memory")
; #define PG8_BAR __builtin_amdgcn_s_barrier()
; #define PG8_SCHED __builtin_amdgcn_sched_barrier(0)
; template <class Epi, class Sched = StaticOrder, class EpiSub = NoSub, bool FAST = false>
; __device__ __forceinline__ void gemm_phase(LAS unsigned char* lds, const Gemm g, const Sched& S, const Epi& E, const EpiSub& ES = EpiSub()) {
;     ...
;             PG8_WAIT_V(8); PG8_WAIT_L(0); PG8_BAR; PG8_MMA(1, 0, At, B0); PG8_MMA(1, 1, At, B1); PG8_BAR; PG8_SCHED;
;             PG8_LDB(B0, 1, 0); PG8_LDB(B1, 1, 1); PG8_SCHED; PG8_LDA(At, 1, 0); PG8_STAGE(PG8_SA(0, 1), a2 + hstepA, voffA);
;             PG8_WAIT_V(8); PG8_WAIT_L(0); PG8_BAR; PG8_MMA(0, 0, At, B0); PG8_MMA(0, 1, At, B1); PG8_BAR; PG8_SCHED;
	v_mfma_f32_16x16x32_bf16 v[60:63], v[100:103], v[174:177], v[60:63]
	v_mfma_f32_16x16x32_bf16 v[56:59], v[124:127], v[174:177], v[56:59]
	v_mfma_f32_16x16x32_bf16 v[44:47], v[100:103], v[194:197], v[44:47]
	v_mfma_f32_16x16x32_bf16 v[40:43], v[124:127], v[194:197], v[40:43]
	v_mfma_f32_16x16x32_bf16 v[28:31], v[100:103], v[202:205], v[28:31]
	v_mfma_f32_16x16x32_bf16 v[24:27], v[124:127], v[202:205], v[24:27]
	v_mfma_f32_16x16x32_bf16 v[12:15], v[100:103], v[210:213], v[12:15]
	v_mfma_f32_16x16x32_bf16 v[8:11], v[124:127], v[210:213], v[8:11]
	v_mfma_f32_16x16x32_bf16 v[60:63], v[112:115], v[178:181], v[60:63]
	v_mfma_f32_16x16x32_bf16 v[56:59], v[136:139], v[178:181], v[56:59]
	v_mfma_f32_16x16x32_bf16 v[44:47], v[112:115], v[198:201], v[44:47]
	v_mfma_f32_16x16x32_bf16 v[40:43], v[136:139], v[198:201], v[40:43]
	v_mfma_f32_16x16x32_bf16 v[28:31], v[112:115], v[206:209], v[28:31]
	v_mfma_f32_16x16x32_bf16 v[24:27], v[136:139], v[206:209], v[24:27]
	v_mfma_f32_16x16x32_bf16 v[12:15], v[112:115], v[214:217], v[12:15]
	v_mfma_f32_16x16x32_bf16 v[8:11], v[136:139], v[214:217], v[8:11]
	v_mfma_f32_16x16x32_bf16 v[52:55], v[144:147], v[174:177], v[52:55]
	v_mfma_f32_16x16x32_bf16 v[48:51], v[152:155], v[174:177], v[48:51]
	v_mfma_f32_16x16x32_bf16 v[36:39], v[144:147], v[194:197], v[36:39]
	v_mfma_f32_16x16x32_bf16 v[32:35], v[152:155], v[194:197], v[32:35]
	v_mfma_f32_16x16x32_bf16 v[20:23], v[144:147], v[202:205], v[20:23]
	v_mfma_f32_16x16x32_bf16 v[16:19], v[152:155], v[202:205], v[16:19]
	v_mfma_f32_16x16x32_bf16 v[4:7], v[144:147], v[210:213], v[4:7]
	v_mfma_f32_16x16x32_bf16 v[0:3], v[152:155], v[210:213], v[0:3]
	v_mfma_f32_16x16x32_bf16 v[52:55], v[148:151], v[178:181], v[52:55]
	v_mfma_f32_16x16x32_bf16 v[48:51], v[170:173], v[178:181], v[48:51]
	v_mfma_f32_16x16x32_bf16 v[36:39], v[148:151], v[198:201], v[36:39]
	v_mfma_f32_16x16x32_bf16 v[32:35], v[170:173], v[198:201], v[32:35]
	v_mfma_f32_16x16x32_bf16 v[20:23], v[148:151], v[206:209], v[20:23]
	v_mfma_f32_16x16x32_bf16 v[16:19], v[170:173], v[206:209], v[16:19]
	v_mfma_f32_16x16x32_bf16 v[4:7], v[148:151], v[214:217], v[4:7]
	v_mfma_f32_16x16x32_bf16 v[0:3], v[170:173], v[214:217], v[0:3]
	s_barrier
	s_setprio 0
	s_add_i32 s50, 0, 0x18000
	s_add_i32 s70, 0, 0x1c000
	v_add_u32_e32 v136, s50, v183
	v_add_u32_e32 v170, s70, v183
	ds_read_b128 v[100:103], v136
	ds_read_b128 v[112:115], v136 offset:1024
	ds_read_b128 v[124:127], v136 offset:2048
	ds_read_b128 v[136:139], v136 offset:3072
	ds_read_b128 v[144:147], v170
	ds_read_b128 v[148:151], v170 offset:1024
	ds_read_b128 v[152:155], v170 offset:2048
	ds_read_b128 v[170:173], v170 offset:3072
	s_add_u32 s52, s52, 0x40000
	s_addc_u32 s53, s53, 0
	s_mov_b32 m0, s57
	v_lshl_add_u64 v[224:225], s[52:53], 0, v[156:157]
	ds_read_b128 v[174:177], v188 offset:32768
	ds_read_b128 v[178:181], v188 offset:33792
	ds_read_b128 v[194:197], v188 offset:34816
	ds_read_b128 v[198:201], v188 offset:35840
	ds_read_b128 v[202:205], v188 offset:36864
	ds_read_b128 v[206:209], v188 offset:37888
	ds_read_b128 v[210:213], v188 offset:38912
	ds_read_b128 v[214:217], v188 offset:39936
	global_load_lds_dwordx4 v[224:225], off
	s_mov_b32 m0, s58
	v_lshl_add_u64 v[224:225], s[52:53], 0, v[160:161]
	global_load_lds_dwordx4 v[224:225], off
	s_waitcnt vmcnt(8)
	s_waitcnt lgkmcnt(0)
	s_setprio 1
	s_barrier
	v_mfma_f32_16x16x32_bf16 v[140:143], v[100:103], v[174:177], v[140:143]
	v_mfma_f32_16x16x32_bf16 v[132:135], v[124:127], v[174:177], v[132:135]
	v_mfma_f32_16x16x32_bf16 v[116:119], v[100:103], v[194:197], v[116:119]
	v_mfma_f32_16x16x32_bf16 v[108:111], v[124:127], v[194:197], v[108:111]
	v_mfma_f32_16x16x32_bf16 v[92:95], v[100:103], v[202:205], v[92:95]
	v_mfma_f32_16x16x32_bf16 v[88:91], v[124:127], v[202:205], v[88:91]
	v_mfma_f32_16x16x32_bf16 v[76:79], v[100:103], v[210:213], v[76:79]
	v_mfma_f32_16x16x32_bf16 v[72:75], v[124:127], v[210:213], v[72:75]
	v_mfma_f32_16x16x32_bf16 v[140:143], v[112:115], v[178:181], v[140:143]
	v_mfma_f32_16x16x32_bf16 v[132:135], v[136:139], v[178:181], v[132:135]
	v_mfma_f32_16x16x32_bf16 v[116:119], v[112:115], v[198:201], v[116:119]
	v_mfma_f32_16x16x32_bf16 v[108:111], v[136:139], v[198:201], v[108:111]
	v_mfma_f32_16x16x32_bf16 v[92:95], v[112:115], v[206:209], v[92:95]
	v_mfma_f32_16x16x32_bf16 v[88:91], v[136:139], v[206:209], v[88:91]
	v_mfma_f32_16x16x32_bf16 v[76:79], v[112:115], v[214:217], v[76:79]
	v_mfma_f32_16x16x32_bf16 v[72:75], v[136:139], v[214:217], v[72:75]
	v_mfma_f32_16x16x32_bf16 v[128:131], v[144:147], v[174:177], v[128:131]
	v_mfma_f32_16x16x32_bf16 v[120:123], v[152:155], v[174:177], v[120:123]
	v_mfma_f32_16x16x32_bf16 v[104:107], v[144:147], v[194:197], v[104:107]
	v_mfma_f32_16x16x32_bf16 v[96:99], v[152:155], v[194:197], v[96:99]
	v_mfma_f32_16x16x32_bf16 v[84:87], v[144:147], v[202:205], v[84:87]
	v_mfma_f32_16x16x32_bf16 v[80:83], v[152:155], v[202:205], v[80:83]
	v_mfma_f32_16x16x32_bf16 v[68:71], v[144:147], v[210:213], v[68:71]
	v_mfma_f32_16x16x32_bf16 v[64:67], v[152:155], v[210:213], v[64:67]
	v_mfma_f32_16x16x32_bf16 v[128:131], v[148:151], v[178:181], v[128:131]
	v_mfma_f32_16x16x32_bf16 v[120:123], v[170:173], v[178:181], v[120:123]
	v_mfma_f32_16x16x32_bf16 v[104:107], v[148:151], v[198:201], v[104:107]
	v_mfma_f32_16x16x32_bf16 v[96:99], v[170:173], v[198:201], v[96:99]
	v_mfma_f32_16x16x32_bf16 v[84:87], v[148:151], v[206:209], v[84:87]
	v_mfma_f32_16x16x32_bf16 v[80:83], v[170:173], v[206:209], v[80:83]
	v_mfma_f32_16x16x32_bf16 v[68:71], v[148:151], v[214:217], v[68:71]
	v_mfma_f32_16x16x32_bf16 v[64:67], v[170:173], v[214:217], v[64:67]
	s_barrier
; #define PG8_STAGE(bufoff, gbase, voff) do { _Pragma("unroll") for (int _i = 0; _i < 2; ++_i) \
;         __builtin_amdgcn_global_load_lds((const unsigned*)((const char*)(gbase) + (voff)[_i]), (LAS unsigned*)(lds + (bufoff) + ldsw + _i * 8192), 16, 0, 0); } while (0)
; #define PG8_LDA(dst, b, h) do { _Pragma("unroll") for (int m = 0; m < 4; ++m) _Pragma("unroll") for (int k = 0; k < 2; ++k) dst[m][k] = *(const LAS bf16x8*)(lds + PG8_SA(b, h) + aoff + m * 2048 + k * 1024); } while (0)
; #define PG8_MMA(ai, bj, At, Bt) do { __builtin_amdgcn_s_setprio(1); _Pragma("unroll") for (int m = 0; m < 4; ++m) _Pragma("unroll") for (int n = 0; n < 2; ++n) _Pragma("unroll") for (int k = 0; k < 2; ++k) \
;         acc[ai][bj][m][n] = __builtin_amdgcn_mfma_f32_16x16x32_bf16(Bt[n][k], At[m][k], acc[ai][bj][m][n], 0, 0, 0); __builtin_amdgcn_s_setprio(0); } while (0)
; #define PG8_WAIT_V(n) asm volatile("s_waitcnt vmcnt(" #n ")" ::: "memory")
; #define PG8_WAIT_L(n) asm volatile("s_waitcnt lgkmcnt(" #n ")" ::: "memory")
; #define PG8_BAR __builtin_amdgcn_s_barrier()
; #define PG8_SCHED __builtin_amdgcn_sched_barrier(0)
; template <class Epi, class Sched = StaticOrder, class EpiSub = NoSub, bool FAST = false>
; __device__ __forceinline__ void gemm_phase(LAS unsigned char* lds, const Gemm g, const Sched& S, const Epi& E, const EpiSub& ES = EpiSub()) {
;     ...
;             PG8_LDA(At, 1, 1); PG8_STAGE(PG8_SB(1, 0), b3, voffB); PG8_STAGE(PG8_SB(1, 1), b3 + hstepB, voffB); PG8_STAGE(PG8_SA(1, 0), a3, voffA);
;             PG8_WAIT_V(8); PG8_WAIT_L(0); PG8_BAR; PG8_MMA(1, 0, At, B0); PG8_MMA(1, 1, At, B1); PG8_BAR; PG8_SCHED;
;     ...
;         if constexpr (FAST && PG8_ALIGN) { if (wr == 0) PG8_BAR; }
	s_setprio 0
	s_add_i32 s50, s50, s54
	v_lshl_add_u64 v[190:191], v[190:191], 0, s[12:13]
	s_mov_b32 m0, s50
	ds_read_b128 v[174:177], v188 offset:49152
	ds_read_b128 v[178:181], v188 offset:50176
	ds_read_b128 v[194:197], v188 offset:51200
	ds_read_b128 v[198:201], v188 offset:52224
	ds_read_b128 v[202:205], v188 offset:53248
	ds_read_b128 v[206:209], v188 offset:54272
	ds_read_b128 v[210:213], v188 offset:55296
	ds_read_b128 v[214:217], v188 offset:56320
	global_load_lds_dwordx4 v[190:191], off
	s_add_i32 m0, s50, 0x2000
	s_add_u32 s42, s42, 0x40080
	v_lshl_add_u64 v[190:191], v[218:219], 0, s[12:13]
	s_addc_u32 s43, s43, 0
	s_add_i32 s50, s70, s54
	global_load_lds_dwordx4 v[190:191], off
	s_mov_b32 m0, s50
	v_lshl_add_u64 v[190:191], s[42:43], 0, v[158:159]
	global_load_lds_dwordx4 v[190:191], off
	s_add_i32 m0, s50, 0x2000
	v_lshl_add_u64 v[190:191], s[42:43], 0, v[162:163]
	global_load_lds_dwordx4 v[190:191], off
	s_mov_b32 m0, s69
	v_lshl_add_u64 v[190:191], v[220:221], 0, s[12:13]
	global_load_lds_dwordx4 v[190:191], off
	s_mov_b32 m0, s74
	v_lshl_add_u64 v[190:191], v[222:223], 0, s[12:13]
	global_load_lds_dwordx4 v[190:191], off
	s_waitcnt vmcnt(8)
	s_waitcnt lgkmcnt(0)
	s_setprio 1
	s_barrier
	v_mfma_f32_16x16x32_bf16 v[60:63], v[100:103], v[174:177], v[60:63]
	v_mfma_f32_16x16x32_bf16 v[56:59], v[124:127], v[174:177], v[56:59]
	v_mfma_f32_16x16x32_bf16 v[44:47], v[100:103], v[194:197], v[44:47]
	v_mfma_f32_16x16x32_bf16 v[40:43], v[124:127], v[194:197], v[40:43]
	v_mfma_f32_16x16x32_bf16 v[28:31], v[100:103], v[202:205], v[28:31]
	v_mfma_f32_16x16x32_bf16 v[24:27], v[124:127], v[202:205], v[24:27]
	v_mfma_f32_16x16x32_bf16 v[12:15], v[100:103], v[210:213], v[12:15]
	v_mfma_f32_16x16x32_bf16 v[8:11], v[124:127], v[210:213], v[8:11]
	v_mfma_f32_16x16x32_bf16 v[60:63], v[112:115], v[178:181], v[60:63]
	v_mfma_f32_16x16x32_bf16 v[56:59], v[136:139], v[178:181], v[56:59]
	v_mfma_f32_16x16x32_bf16 v[44:47], v[112:115], v[198:201], v[44:47]
	v_mfma_f32_16x16x32_bf16 v[40:43], v[136:139], v[198:201], v[40:43]
	v_mfma_f32_16x16x32_bf16 v[28:31], v[112:115], v[206:209], v[28:31]
	v_mfma_f32_16x16x32_bf16 v[24:27], v[136:139], v[206:209], v[24:27]
	v_mfma_f32_16x16x32_bf16 v[12:15], v[112:115], v[214:217], v[12:15]
	v_mfma_f32_16x16x32_bf16 v[8:11], v[136:139], v[214:217], v[8:11]
	v_mfma_f32_16x16x32_bf16 v[52:55], v[144:147], v[174:177], v[52:55]
	v_mfma_f32_16x16x32_bf16 v[48:51], v[152:155], v[174:177], v[48:51]
	v_mfma_f32_16x16x32_bf16 v[36:39], v[144:147], v[194:197], v[36:39]
	v_mfma_f32_16x16x32_bf16 v[32:35], v[152:155], v[194:197], v[32:35]
	v_mfma_f32_16x16x32_bf16 v[20:23], v[144:147], v[202:205], v[20:23]
	v_mfma_f32_16x16x32_bf16 v[16:19], v[152:155], v[202:205], v[16:19]
	v_mfma_f32_16x16x32_bf16 v[4:7], v[144:147], v[210:213], v[4:7]
	v_mfma_f32_16x16x32_bf16 v[0:3], v[152:155], v[210:213], v[0:3]
	v_mfma_f32_16x16x32_bf16 v[52:55], v[148:151], v[178:181], v[52:55]
	v_mfma_f32_16x16x32_bf16 v[48:51], v[170:173], v[178:181], v[48:51]
	v_mfma_f32_16x16x32_bf16 v[36:39], v[148:151], v[198:201], v[36:39]
	v_mfma_f32_16x16x32_bf16 v[32:35], v[170:173], v[198:201], v[32:35]
	v_mfma_f32_16x16x32_bf16 v[20:23], v[148:151], v[206:209], v[20:23]
	v_mfma_f32_16x16x32_bf16 v[16:19], v[170:173], v[206:209], v[16:19]
	v_mfma_f32_16x16x32_bf16 v[4:7], v[148:151], v[214:217], v[4:7]
	v_mfma_f32_16x16x32_bf16 v[0:3], v[170:173], v[214:217], v[0:3]
	s_barrier
	s_setprio 0
	s_add_u32 s40, s40, 0x100
	s_addc_u32 s41, s41, 0
	s_add_u32 s48, s48, 0x100
	s_addc_u32 s49, s49, 0
	s_cmp_ge_u32 s51, s27
	s_mov_b32 s50, s51
	s_cbranch_scc0 .LBB0_600
	s_and_b64 vcc, exec, s[14:15]
	s_cbranch_vccz .LBB0_603
	s_barrier

; #define PG8_STAGE(bufoff, gbase, voff) do { _Pragma("unroll") for (int _i = 0; _i < 2; ++_i) \
;         __builtin_amdgcn_global_load_lds((const unsigned*)((const char*)(gbase) + (voff)[_i]), (LAS unsigned*)(lds + (bufoff) + ldsw + _i * 8192), 16, 0, 0); } while (0)
; #define PG8_LDA(dst, b, h) do { _Pragma("unroll") for (int m = 0; m < 4; ++m) _Pragma("unroll") for (int k = 0; k < 2; ++k) dst[m][k] = *(const LAS bf16x8*)(lds + PG8_SA(b, h) + aoff + m * 2048 + k * 1024); } while (0)
; #define PG8_LDB(dst, b, h) do { _Pragma("unroll") for (int n = 0; n < 2; ++n) _Pragma("unroll") for (int k = 0; k < 2; ++k) dst[n][k] = *(const LAS bf16x8*)(lds + PG8_SB(b, h) + boff + n * 2048 + k * 1024); } while (0)
; #define PG8_MMA(ai, bj, At, Bt) do { __builtin_amdgcn_s_setprio(1); _Pragma("unroll") for (int m = 0; m < 4; ++m) _Pragma("unroll") for (int n = 0; n < 2; ++n) _Pragma("unroll") for (int k = 0; k < 2; ++k) \
;         acc[ai][bj][m][n] = __builtin_amdgcn_mfma_f32_16x16x32_bf16(Bt[n][k], At[m][k], acc[ai][bj][m][n], 0, 0, 0); __builtin_amdgcn_s_setprio(0); } while (0)
; #define PG8_WAIT_V(n) asm volatile("s_waitcnt vmcnt(" #n ")" ::: "memory")
; #define PG8_WAIT_L(n) asm volatile("s_waitcnt lgkmcnt(" #n ")" ::: "memory")
; #define PG8_BAR __builtin_amdgcn_s_barrier()
; #define PG8_SCHED __builtin_amdgcn_sched_barrier(0)
; template <class Epi, class Sched = StaticOrder, class EpiSub = NoSub, bool FAST = false>
; __device__ __forceinline__ void gemm_phase(LAS unsigned char* lds, const Gemm g, const Sched& S, const Epi& E, const EpiSub& ES = EpiSub()) {
;     ...
;         for (int t = 0; t < nt; t += 2) {
;             const bool last = (t == nt - 2);
;             const char* a1 = cA + (size_t)(t + 1) * kstep;
;             const char* a2 = last ? nA : cA + (size_t)(t + 2) * kstep; const char* b2 = last ? nB : cB + (size_t)(t + 2) * kstep;
;             const char* a3 = a2 + kstep; const char* b3 = b2 + kstep;
;             if constexpr (FAST && PG8_SP2) {
;             PG8_LDB(B0, 0, 0); PG8_LDB(B1, 0, 1); PG8_SCHED; PG8_LDA(At, 0, 0); PG8_STAGE(PG8_SA(1, 1), a1 + hstepA, voffA);
;             PG8_WAIT_V(8); PG8_WAIT_L(0); PG8_BAR; PG8_MMA(0, 0, At, B0); PG8_MMA(0, 1, At, B1); PG8_BAR; PG8_SCHED;
;             PG8_LDA(At, 0, 1); PG8_STAGE(PG8_SB(0, 0), b2, voffB); PG8_STAGE(PG8_SB(0, 1), b2 + hstepB, voffB); PG8_STAGE(PG8_SA(0, 0), a2, voffA);
.LBB0_632:
	ds_read_b128 v[104:107], v224
	ds_read_b128 v[108:111], v224 offset:1024
	ds_read_b128 v[120:123], v224 offset:2048
	ds_read_b128 v[124:127], v224 offset:3072
	ds_read_b128 v[136:139], v225
	ds_read_b128 v[140:143], v225 offset:1024
	ds_read_b128 v[152:155], v225 offset:2048
	ds_read_b128 v[156:159], v225 offset:3072
	s_add_i32 s50, s42, 2
	s_add_u32 s40, s38, 0xfff80080
	s_addc_u32 s41, s39, -1
	s_cmp_eq_u32 s33, s42
	s_cselect_b32 s42, s5, s40
	s_cselect_b32 s43, s1, s41
	s_cselect_b32 s41, s21, s49
	s_cselect_b32 s40, s23, s48
	v_lshl_add_u64 v[208:209], s[38:39], 0, v[202:203]
	s_add_i32 m0, s53, 0xc000
	ds_read_b128 v[160:163], v226
	ds_read_b128 v[164:167], v226 offset:1024
	ds_read_b128 v[168:171], v226 offset:2048
	ds_read_b128 v[172:175], v226 offset:3072
	ds_read_b128 v[176:179], v226 offset:4096
	ds_read_b128 v[180:183], v226 offset:5120
	ds_read_b128 v[184:187], v226 offset:6144
	ds_read_b128 v[188:191], v226 offset:7168
	global_load_lds_dwordx4 v[208:209], off
	s_add_i32 m0, s53, 0xe000
	v_lshl_add_u64 v[208:209], s[38:39], 0, v[204:205]
	global_load_lds_dwordx4 v[208:209], off
	s_waitcnt vmcnt(8)
	s_waitcnt lgkmcnt(0)
	s_setprio 1
	s_barrier
	v_mfma_f32_16x16x32_bf16 v[148:151], v[104:107], v[160:163], v[148:151]
	v_mfma_f32_16x16x32_bf16 v[144:147], v[120:123], v[160:163], v[144:147]
	v_mfma_f32_16x16x32_bf16 v[116:119], v[104:107], v[168:171], v[116:119]
	v_mfma_f32_16x16x32_bf16 v[112:115], v[120:123], v[168:171], v[112:115]
	v_mfma_f32_16x16x32_bf16 v[92:95], v[104:107], v[176:179], v[92:95]
	v_mfma_f32_16x16x32_bf16 v[88:91], v[120:123], v[176:179], v[88:91]
	v_mfma_f32_16x16x32_bf16 v[76:79], v[104:107], v[184:187], v[76:79]
	v_mfma_f32_16x16x32_bf16 v[72:75], v[120:123], v[184:187], v[72:75]
	v_mfma_f32_16x16x32_bf16 v[148:151], v[108:111], v[164:167], v[148:151]
	v_mfma_f32_16x16x32_bf16 v[144:147], v[124:127], v[164:167], v[144:147]
	v_mfma_f32_16x16x32_bf16 v[116:119], v[108:111], v[172:175], v[116:119]
	v_mfma_f32_16x16x32_bf16 v[112:115], v[124:127], v[172:175], v[112:115]
	v_mfma_f32_16x16x32_bf16 v[92:95], v[108:111], v[180:183], v[92:95]
	v_mfma_f32_16x16x32_bf16 v[88:91], v[124:127], v[180:183], v[88:91]
	v_mfma_f32_16x16x32_bf16 v[76:79], v[108:111], v[188:191], v[76:79]
	v_mfma_f32_16x16x32_bf16 v[72:75], v[124:127], v[188:191], v[72:75]
	v_mfma_f32_16x16x32_bf16 v[132:135], v[136:139], v[160:163], v[132:135]
	v_mfma_f32_16x16x32_bf16 v[128:131], v[152:155], v[160:163], v[128:131]
	v_mfma_f32_16x16x32_bf16 v[100:103], v[136:139], v[168:171], v[100:103]
	v_mfma_f32_16x16x32_bf16 v[96:99], v[152:155], v[168:171], v[96:99]
	v_mfma_f32_16x16x32_bf16 v[84:87], v[136:139], v[176:179], v[84:87]
	v_mfma_f32_16x16x32_bf16 v[80:83], v[152:155], v[176:179], v[80:83]
	v_mfma_f32_16x16x32_bf16 v[68:71], v[136:139], v[184:187], v[68:71]
	v_mfma_f32_16x16x32_bf16 v[64:67], v[152:155], v[184:187], v[64:67]
	v_mfma_f32_16x16x32_bf16 v[132:135], v[140:143], v[164:167], v[132:135]
	v_mfma_f32_16x16x32_bf16 v[128:131], v[156:159], v[164:167], v[128:131]
	v_mfma_f32_16x16x32_bf16 v[100:103], v[140:143], v[172:175], v[100:103]
	v_mfma_f32_16x16x32_bf16 v[96:99], v[156:159], v[172:175], v[96:99]
	v_mfma_f32_16x16x32_bf16 v[84:87], v[140:143], v[180:183], v[84:87]
	v_mfma_f32_16x16x32_bf16 v[80:83], v[156:159], v[180:183], v[80:83]
	v_mfma_f32_16x16x32_bf16 v[68:71], v[140:143], v[188:191], v[68:71]
	v_mfma_f32_16x16x32_bf16 v[64:67], v[156:159], v[188:191], v[64:67]
	s_barrier
	s_setprio 0
	s_add_i32 s51, s75, s52
	v_lshl_add_u64 v[208:209], s[40:41], 0, v[196:197]
	s_mov_b32 m0, s51
	ds_read_b128 v[160:163], v226 offset:16384
	ds_read_b128 v[164:167], v226 offset:17408
	ds_read_b128 v[168:171], v226 offset:18432
	ds_read_b128 v[172:175], v226 offset:19456
	ds_read_b128 v[176:179], v226 offset:20480
	ds_read_b128 v[180:183], v226 offset:21504
	ds_read_b128 v[184:187], v226 offset:22528
	ds_read_b128 v[188:191], v226 offset:23552
	global_load_lds_dwordx4 v[208:209], off
	s_add_i32 m0, s51, 0x2000
	s_add_u32 s70, s40, 0x80000
	v_lshl_add_u64 v[210:211], s[40:41], 0, v[200:201]
	s_addc_u32 s71, s41, 0
	s_add_i32 s51, s78, s52
	global_load_lds_dwordx4 v[210:211], off
	v_lshl_add_u64 v[212:213], s[70:71], 0, v[196:197]
	s_mov_b32 m0, s51
	v_lshl_add_u64 v[214:215], s[42:43], 0, v[198:199]
	global_load_lds_dwordx4 v[212:213], off
	s_add_i32 m0, s51, 0x2000
	v_lshl_add_u64 v[212:213], s[70:71], 0, v[200:201]
	global_load_lds_dwordx4 v[212:213], off
	s_mov_b32 m0, s53
	v_lshl_add_u64 v[212:213], s[42:43], 0, v[194:195]
	global_load_lds_dwordx4 v[212:213], off
	s_mov_b32 m0, s54
	s_nop 0
	global_load_lds_dwordx4 v[214:215], off
	s_waitcnt vmcnt(8)
	s_waitcnt lgkmcnt(0)
	s_setprio 1
	s_barrier
; #define PG8_STAGE(bufoff, gbase, voff) do { _Pragma("unroll") for (int _i = 0; _i < 2; ++_i) \
;         __builtin_amdgcn_global_load_lds((const unsigned*)((const char*)(gbase) + (voff)[_i]), (LAS unsigned*)(lds + (bufoff) + ldsw + _i * 8192), 16, 0, 0); } while (0)
; #define PG8_LDA(dst, b, h) do { _Pragma("unroll") for (int m = 0; m < 4; ++m) _Pragma("unroll") for (int k = 0; k < 2; ++k) dst[m][k] = *(const LAS bf16x8*)(lds + PG8_SA(b, h) + aoff + m * 2048 + k * 1024); } while (0)
; #define PG8_LDB(dst, b, h) do { _Pragma("unroll") for (int n = 0; n < 2; ++n) _Pragma("unroll") for (int k = 0; k < 2; ++k) dst[n][k] = *(const LAS bf16x8*)(lds + PG8_SB(b, h) + boff + n * 2048 + k * 1024); } while (0)
; #define PG8_MMA(ai, bj, At, Bt) do { __builtin_amdgcn_s_setprio(1); _Pragma("unroll") for (int m = 0; m < 4; ++m) _Pragma("unroll") for (int n = 0; n < 2; ++n) _Pragma("unroll") for (int k = 0; k < 2; ++k) \
;         acc[ai][bj][m][n] = __builtin_amdgcn_mfma_f32_16x16x32_bf16(Bt[n][k], At[m][k], acc[ai][bj][m][n], 0, 0, 0); __builtin_amdgcn_s_setprio(0); } while (0)
; #define PG8_WAIT_V(n) asm volatile("s_waitcnt vmcnt(" #n ")" ::: "memory")
; #define PG8_WAIT_L(n) asm volatile("s_waitcnt lgkmcnt(" #n ")" ::: "memory")
; #define PG8_BAR __builtin_amdgcn_s_barrier()
; #define PG8_SCHED __builtin_amdgcn_sched_barrier(0)
; template <class Epi, class Sched = StaticOrder, class EpiSub = NoSub, bool FAST = false>
; __device__ __forceinline__ void gemm_phase(LAS unsigned char* lds, const Gemm g, const Sched& S, const Epi& E, const EpiSub& ES = EpiSub()) {
;     ...
;             PG8_WAIT_V(8); PG8_WAIT_L(0); PG8_BAR; PG8_MMA(1, 0, At, B0); PG8_MMA(1, 1, At, B1); PG8_BAR; PG8_SCHED;
;             PG8_LDB(B0, 1, 0); PG8_LDB(B1, 1, 1); PG8_SCHED; PG8_LDA(At, 1, 0); PG8_STAGE(PG8_SA(0, 1), a2 + hstepA, voffA);
;             PG8_WAIT_V(8); PG8_WAIT_L(0); PG8_BAR; PG8_MMA(0, 0, At, B0); PG8_MMA(0, 1, At, B1); PG8_BAR; PG8_SCHED;
	v_mfma_f32_16x16x32_bf16 v[60:63], v[104:107], v[160:163], v[60:63]
	v_mfma_f32_16x16x32_bf16 v[56:59], v[120:123], v[160:163], v[56:59]
	v_mfma_f32_16x16x32_bf16 v[44:47], v[104:107], v[168:171], v[44:47]
	v_mfma_f32_16x16x32_bf16 v[40:43], v[120:123], v[168:171], v[40:43]
	v_mfma_f32_16x16x32_bf16 v[28:31], v[104:107], v[176:179], v[28:31]
	v_mfma_f32_16x16x32_bf16 v[24:27], v[120:123], v[176:179], v[24:27]
	v_mfma_f32_16x16x32_bf16 v[12:15], v[104:107], v[184:187], v[12:15]
	v_mfma_f32_16x16x32_bf16 v[8:11], v[120:123], v[184:187], v[8:11]
	v_mfma_f32_16x16x32_bf16 v[60:63], v[108:111], v[164:167], v[60:63]
	v_mfma_f32_16x16x32_bf16 v[56:59], v[124:127], v[164:167], v[56:59]
	v_mfma_f32_16x16x32_bf16 v[44:47], v[108:111], v[172:175], v[44:47]
	v_mfma_f32_16x16x32_bf16 v[40:43], v[124:127], v[172:175], v[40:43]
	v_mfma_f32_16x16x32_bf16 v[28:31], v[108:111], v[180:183], v[28:31]
	v_mfma_f32_16x16x32_bf16 v[24:27], v[124:127], v[180:183], v[24:27]
	v_mfma_f32_16x16x32_bf16 v[12:15], v[108:111], v[188:191], v[12:15]
	v_mfma_f32_16x16x32_bf16 v[8:11], v[124:127], v[188:191], v[8:11]
	v_mfma_f32_16x16x32_bf16 v[52:55], v[136:139], v[160:163], v[52:55]
	v_mfma_f32_16x16x32_bf16 v[48:51], v[152:155], v[160:163], v[48:51]
	v_mfma_f32_16x16x32_bf16 v[36:39], v[136:139], v[168:171], v[36:39]
	v_mfma_f32_16x16x32_bf16 v[32:35], v[152:155], v[168:171], v[32:35]
	v_mfma_f32_16x16x32_bf16 v[20:23], v[136:139], v[176:179], v[20:23]
	v_mfma_f32_16x16x32_bf16 v[16:19], v[152:155], v[176:179], v[16:19]
	v_mfma_f32_16x16x32_bf16 v[4:7], v[136:139], v[184:187], v[4:7]
	v_mfma_f32_16x16x32_bf16 v[0:3], v[152:155], v[184:187], v[0:3]
	v_mfma_f32_16x16x32_bf16 v[52:55], v[140:143], v[164:167], v[52:55]
	v_mfma_f32_16x16x32_bf16 v[48:51], v[156:159], v[164:167], v[48:51]
	v_mfma_f32_16x16x32_bf16 v[36:39], v[140:143], v[172:175], v[36:39]
	v_mfma_f32_16x16x32_bf16 v[32:35], v[156:159], v[172:175], v[32:35]
	v_mfma_f32_16x16x32_bf16 v[20:23], v[140:143], v[180:183], v[20:23]
	v_mfma_f32_16x16x32_bf16 v[16:19], v[156:159], v[180:183], v[16:19]
	v_mfma_f32_16x16x32_bf16 v[4:7], v[140:143], v[188:191], v[4:7]
	v_mfma_f32_16x16x32_bf16 v[0:3], v[156:159], v[188:191], v[0:3]
	s_barrier
	s_setprio 0
	s_add_i32 s51, 0, 0x18000
	s_add_i32 s70, 0, 0x1c000
	v_add_u32_e32 v124, s51, v221
	v_add_u32_e32 v156, s70, v221
	ds_read_b128 v[104:107], v124
	ds_read_b128 v[108:111], v124 offset:1024
	ds_read_b128 v[120:123], v124 offset:2048
	ds_read_b128 v[124:127], v124 offset:3072
	ds_read_b128 v[136:139], v156
	ds_read_b128 v[140:143], v156 offset:1024
	ds_read_b128 v[152:155], v156 offset:2048
	ds_read_b128 v[156:159], v156 offset:3072
	s_add_u32 s42, s42, 0x80000
	s_addc_u32 s43, s43, 0
	s_mov_b32 m0, s55
	v_lshl_add_u64 v[216:217], s[42:43], 0, v[194:195]
	ds_read_b128 v[160:163], v226 offset:32768
	ds_read_b128 v[164:167], v226 offset:33792
	ds_read_b128 v[168:171], v226 offset:34816
	ds_read_b128 v[172:175], v226 offset:35840
	ds_read_b128 v[176:179], v226 offset:36864
	ds_read_b128 v[180:183], v226 offset:37888
	ds_read_b128 v[184:187], v226 offset:38912
	ds_read_b128 v[188:191], v226 offset:39936
	global_load_lds_dwordx4 v[216:217], off
	s_mov_b32 m0, s56
	v_lshl_add_u64 v[216:217], s[42:43], 0, v[198:199]
	global_load_lds_dwordx4 v[216:217], off
	s_waitcnt vmcnt(8)
	s_waitcnt lgkmcnt(0)
	s_setprio 1
	s_barrier
	v_mfma_f32_16x16x32_bf16 v[148:151], v[104:107], v[160:163], v[148:151]
	v_mfma_f32_16x16x32_bf16 v[144:147], v[120:123], v[160:163], v[144:147]
	v_mfma_f32_16x16x32_bf16 v[116:119], v[104:107], v[168:171], v[116:119]
	v_mfma_f32_16x16x32_bf16 v[112:115], v[120:123], v[168:171], v[112:115]
	v_mfma_f32_16x16x32_bf16 v[92:95], v[104:107], v[176:179], v[92:95]
	v_mfma_f32_16x16x32_bf16 v[88:91], v[120:123], v[176:179], v[88:91]
	v_mfma_f32_16x16x32_bf16 v[76:79], v[104:107], v[184:187], v[76:79]
	v_mfma_f32_16x16x32_bf16 v[72:75], v[120:123], v[184:187], v[72:75]
	v_mfma_f32_16x16x32_bf16 v[148:151], v[108:111], v[164:167], v[148:151]
	v_mfma_f32_16x16x32_bf16 v[144:147], v[124:127], v[164:167], v[144:147]
	v_mfma_f32_16x16x32_bf16 v[116:119], v[108:111], v[172:175], v[116:119]
	v_mfma_f32_16x16x32_bf16 v[112:115], v[124:127], v[172:175], v[112:115]
	v_mfma_f32_16x16x32_bf16 v[92:95], v[108:111], v[180:183], v[92:95]
	v_mfma_f32_16x16x32_bf16 v[88:91], v[124:127], v[180:183], v[88:91]
	v_mfma_f32_16x16x32_bf16 v[76:79], v[108:111], v[188:191], v[76:79]
	v_mfma_f32_16x16x32_bf16 v[72:75], v[124:127], v[188:191], v[72:75]
	v_mfma_f32_16x16x32_bf16 v[132:135], v[136:139], v[160:163], v[132:135]
	v_mfma_f32_16x16x32_bf16 v[128:131], v[152:155], v[160:163], v[128:131]
	v_mfma_f32_16x16x32_bf16 v[100:103], v[136:139], v[168:171], v[100:103]
	v_mfma_f32_16x16x32_bf16 v[96:99], v[152:155], v[168:171], v[96:99]
	v_mfma_f32_16x16x32_bf16 v[84:87], v[136:139], v[176:179], v[84:87]
	v_mfma_f32_16x16x32_bf16 v[80:83], v[152:155], v[176:179], v[80:83]
	v_mfma_f32_16x16x32_bf16 v[68:71], v[136:139], v[184:187], v[68:71]
	v_mfma_f32_16x16x32_bf16 v[64:67], v[152:155], v[184:187], v[64:67]
	v_mfma_f32_16x16x32_bf16 v[132:135], v[140:143], v[164:167], v[132:135]
	v_mfma_f32_16x16x32_bf16 v[128:131], v[156:159], v[164:167], v[128:131]
	v_mfma_f32_16x16x32_bf16 v[100:103], v[140:143], v[172:175], v[100:103]
	v_mfma_f32_16x16x32_bf16 v[96:99], v[156:159], v[172:175], v[96:99]
	v_mfma_f32_16x16x32_bf16 v[84:87], v[140:143], v[180:183], v[84:87]
	v_mfma_f32_16x16x32_bf16 v[80:83], v[156:159], v[180:183], v[80:83]
	v_mfma_f32_16x16x32_bf16 v[68:71], v[140:143], v[188:191], v[68:71]
	v_mfma_f32_16x16x32_bf16 v[64:67], v[156:159], v[188:191], v[64:67]
	s_barrier
; #define PG8_STAGE(bufoff, gbase, voff) do { _Pragma("unroll") for (int _i = 0; _i < 2; ++_i) \
;         __builtin_amdgcn_global_load_lds((const unsigned*)((const char*)(gbase) + (voff)[_i]), (LAS unsigned*)(lds + (bufoff) + ldsw + _i * 8192), 16, 0, 0); } while (0)
; #define PG8_LDA(dst, b, h) do { _Pragma("unroll") for (int m = 0; m < 4; ++m) _Pragma("unroll") for (int k = 0; k < 2; ++k) dst[m][k] = *(const LAS bf16x8*)(lds + PG8_SA(b, h) + aoff + m * 2048 + k * 1024); } while (0)
; #define PG8_MMA(ai, bj, At, Bt) do { __builtin_amdgcn_s_setprio(1); _Pragma("unroll") for (int m = 0; m < 4; ++m) _Pragma("unroll") for (int n = 0; n < 2; ++n) _Pragma("unroll") for (int k = 0; k < 2; ++k) \
;         acc[ai][bj][m][n] = __builtin_amdgcn_mfma_f32_16x16x32_bf16(Bt[n][k], At[m][k], acc[ai][bj][m][n], 0, 0, 0); __builtin_amdgcn_s_setprio(0); } while (0)
; #define PG8_WAIT_V(n) asm volatile("s_waitcnt vmcnt(" #n ")" ::: "memory")
; #define PG8_WAIT_L(n) asm volatile("s_waitcnt lgkmcnt(" #n ")" ::: "memory")
; #define PG8_BAR __builtin_amdgcn_s_barrier()
; #define PG8_SCHED __builtin_amdgcn_sched_barrier(0)
; template <class Epi, class Sched = StaticOrder, class EpiSub = NoSub, bool FAST = false>
; __device__ __forceinline__ void gemm_phase(LAS unsigned char* lds, const Gemm g, const Sched& S, const Epi& E, const EpiSub& ES = EpiSub()) {
;     ...
;             PG8_LDA(At, 1, 1); PG8_STAGE(PG8_SB(1, 0), b3, voffB); PG8_STAGE(PG8_SB(1, 1), b3 + hstepB, voffB); PG8_STAGE(PG8_SA(1, 0), a3, voffA);
;             PG8_WAIT_V(8); PG8_WAIT_L(0); PG8_BAR; PG8_MMA(1, 0, At, B0); PG8_MMA(1, 1, At, B1); PG8_BAR; PG8_SCHED;
;     ...
;         if constexpr (FAST && PG8_ALIGN) { if (wr == 0) PG8_BAR; }
	s_setprio 0
	s_add_i32 s42, s51, s52
	v_lshl_add_u64 v[208:209], v[208:209], 0, s[12:13]
	s_mov_b32 m0, s42
	ds_read_b128 v[160:163], v226 offset:49152
	ds_read_b128 v[164:167], v226 offset:50176
	ds_read_b128 v[168:171], v226 offset:51200
	ds_read_b128 v[172:175], v226 offset:52224
	ds_read_b128 v[176:179], v226 offset:53248
	ds_read_b128 v[180:183], v226 offset:54272
	ds_read_b128 v[184:187], v226 offset:55296
	ds_read_b128 v[188:191], v226 offset:56320
	global_load_lds_dwordx4 v[208:209], off
	s_add_i32 m0, s42, 0x2000
	s_add_u32 s40, s40, 0x80080
	v_lshl_add_u64 v[208:209], v[210:211], 0, s[12:13]
	s_addc_u32 s41, s41, 0
	s_add_i32 s42, s70, s52
	global_load_lds_dwordx4 v[208:209], off
	s_mov_b32 m0, s42
	v_lshl_add_u64 v[208:209], s[40:41], 0, v[196:197]
	global_load_lds_dwordx4 v[208:209], off
	s_add_i32 m0, s42, 0x2000
	v_lshl_add_u64 v[208:209], s[40:41], 0, v[200:201]
	global_load_lds_dwordx4 v[208:209], off
	s_mov_b32 m0, s69
	v_lshl_add_u64 v[208:209], v[212:213], 0, s[12:13]
	global_load_lds_dwordx4 v[208:209], off
	s_mov_b32 m0, s74
	v_lshl_add_u64 v[208:209], v[214:215], 0, s[12:13]
	global_load_lds_dwordx4 v[208:209], off
	s_waitcnt vmcnt(8)
	s_waitcnt lgkmcnt(0)
	s_setprio 1
	s_barrier
	v_mfma_f32_16x16x32_bf16 v[60:63], v[104:107], v[160:163], v[60:63]
	v_mfma_f32_16x16x32_bf16 v[56:59], v[120:123], v[160:163], v[56:59]
	v_mfma_f32_16x16x32_bf16 v[44:47], v[104:107], v[168:171], v[44:47]
	v_mfma_f32_16x16x32_bf16 v[40:43], v[120:123], v[168:171], v[40:43]
	v_mfma_f32_16x16x32_bf16 v[28:31], v[104:107], v[176:179], v[28:31]
	v_mfma_f32_16x16x32_bf16 v[24:27], v[120:123], v[176:179], v[24:27]
	v_mfma_f32_16x16x32_bf16 v[12:15], v[104:107], v[184:187], v[12:15]
	v_mfma_f32_16x16x32_bf16 v[8:11], v[120:123], v[184:187], v[8:11]
	v_mfma_f32_16x16x32_bf16 v[60:63], v[108:111], v[164:167], v[60:63]
	v_mfma_f32_16x16x32_bf16 v[56:59], v[124:127], v[164:167], v[56:59]
	v_mfma_f32_16x16x32_bf16 v[44:47], v[108:111], v[172:175], v[44:47]
	v_mfma_f32_16x16x32_bf16 v[40:43], v[124:127], v[172:175], v[40:43]
	v_mfma_f32_16x16x32_bf16 v[28:31], v[108:111], v[180:183], v[28:31]
	v_mfma_f32_16x16x32_bf16 v[24:27], v[124:127], v[180:183], v[24:27]
	v_mfma_f32_16x16x32_bf16 v[12:15], v[108:111], v[188:191], v[12:15]
	v_mfma_f32_16x16x32_bf16 v[8:11], v[124:127], v[188:191], v[8:11]
	v_mfma_f32_16x16x32_bf16 v[52:55], v[136:139], v[160:163], v[52:55]
	v_mfma_f32_16x16x32_bf16 v[48:51], v[152:155], v[160:163], v[48:51]
	v_mfma_f32_16x16x32_bf16 v[36:39], v[136:139], v[168:171], v[36:39]
	v_mfma_f32_16x16x32_bf16 v[32:35], v[152:155], v[168:171], v[32:35]
	v_mfma_f32_16x16x32_bf16 v[20:23], v[136:139], v[176:179], v[20:23]
	v_mfma_f32_16x16x32_bf16 v[16:19], v[152:155], v[176:179], v[16:19]
	v_mfma_f32_16x16x32_bf16 v[4:7], v[136:139], v[184:187], v[4:7]
	v_mfma_f32_16x16x32_bf16 v[0:3], v[152:155], v[184:187], v[0:3]
	v_mfma_f32_16x16x32_bf16 v[52:55], v[140:143], v[164:167], v[52:55]
	v_mfma_f32_16x16x32_bf16 v[48:51], v[156:159], v[164:167], v[48:51]
	v_mfma_f32_16x16x32_bf16 v[36:39], v[140:143], v[172:175], v[36:39]
	v_mfma_f32_16x16x32_bf16 v[32:35], v[156:159], v[172:175], v[32:35]
	v_mfma_f32_16x16x32_bf16 v[20:23], v[140:143], v[180:183], v[20:23]
	v_mfma_f32_16x16x32_bf16 v[16:19], v[156:159], v[180:183], v[16:19]
	v_mfma_f32_16x16x32_bf16 v[4:7], v[140:143], v[188:191], v[4:7]
	v_mfma_f32_16x16x32_bf16 v[0:3], v[156:159], v[188:191], v[0:3]
	s_barrier
	s_setprio 0
	s_add_u32 s38, s38, 0x100
	s_addc_u32 s39, s39, 0
	s_add_u32 s48, s48, 0x100
	s_addc_u32 s49, s49, 0
	s_cmp_ge_u32 s50, s31
	s_mov_b32 s42, s50
	s_cbranch_scc0 .LBB0_632
	s_and_b64 vcc, exec, s[14:15]
	s_cbranch_vccz .LBB0_635
	s_barrier

; #define PG8_STAGE(bufoff, gbase, voff) do { _Pragma("unroll") for (int _i = 0; _i < 2; ++_i) \
;         __builtin_amdgcn_global_load_lds((const unsigned*)((const char*)(gbase) + (voff)[_i]), (LAS unsigned*)(lds + (bufoff) + ldsw + _i * 8192), 16, 0, 0); } while (0)
; #define PG8_LDA(dst, b, h) do { _Pragma("unroll") for (int m = 0; m < 4; ++m) _Pragma("unroll") for (int k = 0; k < 2; ++k) dst[m][k] = *(const LAS bf16x8*)(lds + PG8_SA(b, h) + aoff + m * 2048 + k * 1024); } while (0)
; #define PG8_LDB(dst, b, h) do { _Pragma("unroll") for (int n = 0; n < 2; ++n) _Pragma("unroll") for (int k = 0; k < 2; ++k) dst[n][k] = *(const LAS bf16x8*)(lds + PG8_SB(b, h) + boff + n * 2048 + k * 1024); } while (0)
; #define PG8_MMA(ai, bj, At, Bt) do { __builtin_amdgcn_s_setprio(1); _Pragma("unroll") for (int m = 0; m < 4; ++m) _Pragma("unroll") for (int n = 0; n < 2; ++n) _Pragma("unroll") for (int k = 0; k < 2; ++k) \
;         acc[ai][bj][m][n] = __builtin_amdgcn_mfma_f32_16x16x32_bf16(Bt[n][k], At[m][k], acc[ai][bj][m][n], 0, 0, 0); __builtin_amdgcn_s_setprio(0); } while (0)
; #define PG8_WAIT_V(n) asm volatile("s_waitcnt vmcnt(" #n ")" ::: "memory")
; #define PG8_WAIT_L(n) asm volatile("s_waitcnt lgkmcnt(" #n ")" ::: "memory")
; #define PG8_BAR __builtin_amdgcn_s_barrier()
; #define PG8_SCHED __builtin_amdgcn_sched_barrier(0)
; template <class Epi, class Sched = StaticOrder, class EpiSub = NoSub, bool FAST = false>
; __device__ __forceinline__ void gemm_phase(LAS unsigned char* lds, const Gemm g, const Sched& S, const Epi& E, const EpiSub& ES = EpiSub()) {
;     ...
;         for (int t = 0; t < nt; t += 2) {
;             const bool last = (t == nt - 2);
;             const char* a1 = cA + (size_t)(t + 1) * kstep;
;             const char* a2 = last ? nA : cA + (size_t)(t + 2) * kstep; const char* b2 = last ? nB : cB + (size_t)(t + 2) * kstep;
;             const char* a3 = a2 + kstep; const char* b3 = b2 + kstep;
;             if constexpr (FAST && PG8_SP2) {
;             PG8_LDB(B0, 0, 0); PG8_LDB(B1, 0, 1); PG8_SCHED; PG8_LDA(At, 0, 0); PG8_STAGE(PG8_SA(1, 1), a1 + hstepA, voffA);
;             PG8_WAIT_V(8); PG8_WAIT_L(0); PG8_BAR; PG8_MMA(0, 0, At, B0); PG8_MMA(0, 1, At, B1); PG8_BAR; PG8_SCHED;
;             PG8_LDA(At, 0, 1); PG8_STAGE(PG8_SB(0, 0), b2, voffB); PG8_STAGE(PG8_SB(0, 1), b2 + hstepB, voffB); PG8_STAGE(PG8_SA(0, 0), a2, voffA);
.LBB0_769:
	ds_read_b128 v[96:99], v215
	ds_read_b128 v[100:103], v215 offset:1024
	ds_read_b128 v[112:115], v215 offset:2048
	ds_read_b128 v[116:119], v215 offset:3072
	ds_read_b128 v[144:147], v216
	ds_read_b128 v[148:151], v216 offset:1024
	ds_read_b128 v[152:155], v216 offset:2048
	ds_read_b128 v[156:159], v216 offset:3072
	s_add_i32 s72, s42, 2
	s_add_u32 s40, s38, 0xfff80080
	s_addc_u32 s41, s39, -1
	s_cmp_eq_u32 s33, s42
	s_cselect_b32 s42, s5, s40
	s_cselect_b32 s43, s1, s41
	s_cselect_b32 s41, s19, s71
	s_cselect_b32 s40, s21, s70
	v_lshl_add_u64 v[208:209], s[38:39], 0, v[194:195]
	s_add_i32 m0, s48, 0xc000
	ds_read_b128 v[160:163], v217
	ds_read_b128 v[164:167], v217 offset:1024
	ds_read_b128 v[168:171], v217 offset:2048
	ds_read_b128 v[172:175], v217 offset:3072
	ds_read_b128 v[176:179], v217 offset:4096
	ds_read_b128 v[180:183], v217 offset:5120
	ds_read_b128 v[200:203], v217 offset:6144
	ds_read_b128 v[204:207], v217 offset:7168
	global_load_lds_dwordx4 v[208:209], off
	s_add_i32 m0, s48, 0xe000
	v_lshl_add_u64 v[208:209], s[38:39], 0, v[196:197]
	global_load_lds_dwordx4 v[208:209], off
	s_waitcnt vmcnt(8)
	s_waitcnt lgkmcnt(0)
	s_setprio 1
	s_barrier
	v_mfma_f32_16x16x32_bf16 v[140:143], v[96:99], v[160:163], v[140:143]
	v_mfma_f32_16x16x32_bf16 v[136:139], v[112:115], v[160:163], v[136:139]
	v_mfma_f32_16x16x32_bf16 v[124:127], v[96:99], v[168:171], v[124:127]
	v_mfma_f32_16x16x32_bf16 v[120:123], v[112:115], v[168:171], v[120:123]
	v_mfma_f32_16x16x32_bf16 v[92:95], v[96:99], v[176:179], v[92:95]
	v_mfma_f32_16x16x32_bf16 v[88:91], v[112:115], v[176:179], v[88:91]
	v_mfma_f32_16x16x32_bf16 v[76:79], v[96:99], v[200:203], v[76:79]
	v_mfma_f32_16x16x32_bf16 v[72:75], v[112:115], v[200:203], v[72:75]
	v_mfma_f32_16x16x32_bf16 v[140:143], v[100:103], v[164:167], v[140:143]
	v_mfma_f32_16x16x32_bf16 v[136:139], v[116:119], v[164:167], v[136:139]
	v_mfma_f32_16x16x32_bf16 v[124:127], v[100:103], v[172:175], v[124:127]
	v_mfma_f32_16x16x32_bf16 v[120:123], v[116:119], v[172:175], v[120:123]
	v_mfma_f32_16x16x32_bf16 v[92:95], v[100:103], v[180:183], v[92:95]
	v_mfma_f32_16x16x32_bf16 v[88:91], v[116:119], v[180:183], v[88:91]
	v_mfma_f32_16x16x32_bf16 v[76:79], v[100:103], v[204:207], v[76:79]
	v_mfma_f32_16x16x32_bf16 v[72:75], v[116:119], v[204:207], v[72:75]
	v_mfma_f32_16x16x32_bf16 v[132:135], v[144:147], v[160:163], v[132:135]
	v_mfma_f32_16x16x32_bf16 v[128:131], v[152:155], v[160:163], v[128:131]
	v_mfma_f32_16x16x32_bf16 v[108:111], v[144:147], v[168:171], v[108:111]
	v_mfma_f32_16x16x32_bf16 v[104:107], v[152:155], v[168:171], v[104:107]
	v_mfma_f32_16x16x32_bf16 v[84:87], v[144:147], v[176:179], v[84:87]
	v_mfma_f32_16x16x32_bf16 v[80:83], v[152:155], v[176:179], v[80:83]
	v_mfma_f32_16x16x32_bf16 v[68:71], v[144:147], v[200:203], v[68:71]
	v_mfma_f32_16x16x32_bf16 v[64:67], v[152:155], v[200:203], v[64:67]
	v_mfma_f32_16x16x32_bf16 v[132:135], v[148:151], v[164:167], v[132:135]
	v_mfma_f32_16x16x32_bf16 v[128:131], v[156:159], v[164:167], v[128:131]
	v_mfma_f32_16x16x32_bf16 v[108:111], v[148:151], v[172:175], v[108:111]
	v_mfma_f32_16x16x32_bf16 v[104:107], v[156:159], v[172:175], v[104:107]
	v_mfma_f32_16x16x32_bf16 v[84:87], v[148:151], v[180:183], v[84:87]
	v_mfma_f32_16x16x32_bf16 v[80:83], v[156:159], v[180:183], v[80:83]
	v_mfma_f32_16x16x32_bf16 v[68:71], v[148:151], v[204:207], v[68:71]
	v_mfma_f32_16x16x32_bf16 v[64:67], v[156:159], v[204:207], v[64:67]
	s_barrier
	s_setprio 0
	s_add_i32 s73, s58, s17
	v_lshl_add_u64 v[208:209], s[40:41], 0, v[186:187]
	s_mov_b32 m0, s73
	ds_read_b128 v[160:163], v217 offset:16384
	ds_read_b128 v[164:167], v217 offset:17408
	ds_read_b128 v[168:171], v217 offset:18432
	ds_read_b128 v[172:175], v217 offset:19456
	ds_read_b128 v[176:179], v217 offset:20480
	ds_read_b128 v[180:183], v217 offset:21504
	ds_read_b128 v[200:203], v217 offset:22528
	ds_read_b128 v[204:207], v217 offset:23552
	global_load_lds_dwordx4 v[208:209], off
	s_add_i32 m0, s73, 0x2000
	s_add_u32 s76, s40, 0x80000
	v_lshl_add_u64 v[210:211], s[40:41], 0, v[190:191]
	s_addc_u32 s77, s41, 0
	s_add_i32 s73, s59, s17
	global_load_lds_dwordx4 v[210:211], off
	v_lshl_add_u64 v[218:219], s[76:77], 0, v[186:187]
	s_mov_b32 m0, s73
	v_lshl_add_u64 v[220:221], s[42:43], 0, v[188:189]
	global_load_lds_dwordx4 v[218:219], off
	s_add_i32 m0, s73, 0x2000
	v_lshl_add_u64 v[218:219], s[76:77], 0, v[190:191]
	global_load_lds_dwordx4 v[218:219], off
	s_mov_b32 m0, s48
	v_lshl_add_u64 v[218:219], s[42:43], 0, v[184:185]
	global_load_lds_dwordx4 v[218:219], off
	s_mov_b32 m0, s49
	s_nop 0
	global_load_lds_dwordx4 v[220:221], off
	s_waitcnt vmcnt(8)
	s_waitcnt lgkmcnt(0)
	s_setprio 1
	s_barrier
; #define PG8_STAGE(bufoff, gbase, voff) do { _Pragma("unroll") for (int _i = 0; _i < 2; ++_i) \
;         __builtin_amdgcn_global_load_lds((const unsigned*)((const char*)(gbase) + (voff)[_i]), (LAS unsigned*)(lds + (bufoff) + ldsw + _i * 8192), 16, 0, 0); } while (0)
; #define PG8_LDA(dst, b, h) do { _Pragma("unroll") for (int m = 0; m < 4; ++m) _Pragma("unroll") for (int k = 0; k < 2; ++k) dst[m][k] = *(const LAS bf16x8*)(lds + PG8_SA(b, h) + aoff + m * 2048 + k * 1024); } while (0)
; #define PG8_LDB(dst, b, h) do { _Pragma("unroll") for (int n = 0; n < 2; ++n) _Pragma("unroll") for (int k = 0; k < 2; ++k) dst[n][k] = *(const LAS bf16x8*)(lds + PG8_SB(b, h) + boff + n * 2048 + k * 1024); } while (0)
; #define PG8_MMA(ai, bj, At, Bt) do { __builtin_amdgcn_s_setprio(1); _Pragma("unroll") for (int m = 0; m < 4; ++m) _Pragma("unroll") for (int n = 0; n < 2; ++n) _Pragma("unroll") for (int k = 0; k < 2; ++k) \
;         acc[ai][bj][m][n] = __builtin_amdgcn_mfma_f32_16x16x32_bf16(Bt[n][k], At[m][k], acc[ai][bj][m][n], 0, 0, 0); __builtin_amdgcn_s_setprio(0); } while (0)
; #define PG8_WAIT_V(n) asm volatile("s_waitcnt vmcnt(" #n ")" ::: "memory")
; #define PG8_WAIT_L(n) asm volatile("s_waitcnt lgkmcnt(" #n ")" ::: "memory")
; #define PG8_BAR __builtin_amdgcn_s_barrier()
; #define PG8_SCHED __builtin_amdgcn_sched_barrier(0)
; template <class Epi, class Sched = StaticOrder, class EpiSub = NoSub, bool FAST = false>
; __device__ __forceinline__ void gemm_phase(LAS unsigned char* lds, const Gemm g, const Sched& S, const Epi& E, const EpiSub& ES = EpiSub()) {
;     ...
;             PG8_WAIT_V(8); PG8_WAIT_L(0); PG8_BAR; PG8_MMA(1, 0, At, B0); PG8_MMA(1, 1, At, B1); PG8_BAR; PG8_SCHED;
;             PG8_LDB(B0, 1, 0); PG8_LDB(B1, 1, 1); PG8_SCHED; PG8_LDA(At, 1, 0); PG8_STAGE(PG8_SA(0, 1), a2 + hstepA, voffA);
;             PG8_WAIT_V(8); PG8_WAIT_L(0); PG8_BAR; PG8_MMA(0, 0, At, B0); PG8_MMA(0, 1, At, B1); PG8_BAR; PG8_SCHED;
	v_mfma_f32_16x16x32_bf16 v[60:63], v[96:99], v[160:163], v[60:63]
	v_mfma_f32_16x16x32_bf16 v[56:59], v[112:115], v[160:163], v[56:59]
	v_mfma_f32_16x16x32_bf16 v[44:47], v[96:99], v[168:171], v[44:47]
	v_mfma_f32_16x16x32_bf16 v[40:43], v[112:115], v[168:171], v[40:43]
	v_mfma_f32_16x16x32_bf16 v[28:31], v[96:99], v[176:179], v[28:31]
	v_mfma_f32_16x16x32_bf16 v[24:27], v[112:115], v[176:179], v[24:27]
	v_mfma_f32_16x16x32_bf16 v[12:15], v[96:99], v[200:203], v[12:15]
	v_mfma_f32_16x16x32_bf16 v[8:11], v[112:115], v[200:203], v[8:11]
	v_mfma_f32_16x16x32_bf16 v[60:63], v[100:103], v[164:167], v[60:63]
	v_mfma_f32_16x16x32_bf16 v[56:59], v[116:119], v[164:167], v[56:59]
	v_mfma_f32_16x16x32_bf16 v[44:47], v[100:103], v[172:175], v[44:47]
	v_mfma_f32_16x16x32_bf16 v[40:43], v[116:119], v[172:175], v[40:43]
	v_mfma_f32_16x16x32_bf16 v[28:31], v[100:103], v[180:183], v[28:31]
	v_mfma_f32_16x16x32_bf16 v[24:27], v[116:119], v[180:183], v[24:27]
	v_mfma_f32_16x16x32_bf16 v[12:15], v[100:103], v[204:207], v[12:15]
	v_mfma_f32_16x16x32_bf16 v[8:11], v[116:119], v[204:207], v[8:11]
	v_mfma_f32_16x16x32_bf16 v[52:55], v[144:147], v[160:163], v[52:55]
	v_mfma_f32_16x16x32_bf16 v[48:51], v[152:155], v[160:163], v[48:51]
	v_mfma_f32_16x16x32_bf16 v[36:39], v[144:147], v[168:171], v[36:39]
	v_mfma_f32_16x16x32_bf16 v[32:35], v[152:155], v[168:171], v[32:35]
	v_mfma_f32_16x16x32_bf16 v[20:23], v[144:147], v[176:179], v[20:23]
	v_mfma_f32_16x16x32_bf16 v[16:19], v[152:155], v[176:179], v[16:19]
	v_mfma_f32_16x16x32_bf16 v[4:7], v[144:147], v[200:203], v[4:7]
	v_mfma_f32_16x16x32_bf16 v[0:3], v[152:155], v[200:203], v[0:3]
	v_mfma_f32_16x16x32_bf16 v[52:55], v[148:151], v[164:167], v[52:55]
	v_mfma_f32_16x16x32_bf16 v[48:51], v[156:159], v[164:167], v[48:51]
	v_mfma_f32_16x16x32_bf16 v[36:39], v[148:151], v[172:175], v[36:39]
	v_mfma_f32_16x16x32_bf16 v[32:35], v[156:159], v[172:175], v[32:35]
	v_mfma_f32_16x16x32_bf16 v[20:23], v[148:151], v[180:183], v[20:23]
	v_mfma_f32_16x16x32_bf16 v[16:19], v[156:159], v[180:183], v[16:19]
	v_mfma_f32_16x16x32_bf16 v[4:7], v[148:151], v[204:207], v[4:7]
	v_mfma_f32_16x16x32_bf16 v[0:3], v[156:159], v[204:207], v[0:3]
	s_barrier
	s_setprio 0
	s_add_i32 s73, 0, 0x18000
	s_add_i32 s76, 0, 0x1c000
	v_add_u32_e32 v116, s73, v212
	v_add_u32_e32 v156, s76, v212
	ds_read_b128 v[96:99], v116
	ds_read_b128 v[100:103], v116 offset:1024
	ds_read_b128 v[112:115], v116 offset:2048
	ds_read_b128 v[116:119], v116 offset:3072
	ds_read_b128 v[144:147], v156
	ds_read_b128 v[148:151], v156 offset:1024
	ds_read_b128 v[152:155], v156 offset:2048
	ds_read_b128 v[156:159], v156 offset:3072
	s_add_u32 s42, s42, 0x80000
	s_addc_u32 s43, s43, 0
	s_mov_b32 m0, s50
	v_lshl_add_u64 v[222:223], s[42:43], 0, v[184:185]
	ds_read_b128 v[160:163], v217 offset:32768
	ds_read_b128 v[164:167], v217 offset:33792
	ds_read_b128 v[168:171], v217 offset:34816
	ds_read_b128 v[172:175], v217 offset:35840
	ds_read_b128 v[176:179], v217 offset:36864
	ds_read_b128 v[180:183], v217 offset:37888
	ds_read_b128 v[200:203], v217 offset:38912
	ds_read_b128 v[204:207], v217 offset:39936
	global_load_lds_dwordx4 v[222:223], off
	s_mov_b32 m0, s51
	v_lshl_add_u64 v[222:223], s[42:43], 0, v[188:189]
	global_load_lds_dwordx4 v[222:223], off
	s_waitcnt vmcnt(8)
	s_waitcnt lgkmcnt(0)
	s_setprio 1
	s_barrier
	v_mfma_f32_16x16x32_bf16 v[140:143], v[96:99], v[160:163], v[140:143]
	v_mfma_f32_16x16x32_bf16 v[136:139], v[112:115], v[160:163], v[136:139]
	v_mfma_f32_16x16x32_bf16 v[124:127], v[96:99], v[168:171], v[124:127]
	v_mfma_f32_16x16x32_bf16 v[120:123], v[112:115], v[168:171], v[120:123]
	v_mfma_f32_16x16x32_bf16 v[92:95], v[96:99], v[176:179], v[92:95]
	v_mfma_f32_16x16x32_bf16 v[88:91], v[112:115], v[176:179], v[88:91]
	v_mfma_f32_16x16x32_bf16 v[76:79], v[96:99], v[200:203], v[76:79]
	v_mfma_f32_16x16x32_bf16 v[72:75], v[112:115], v[200:203], v[72:75]
	v_mfma_f32_16x16x32_bf16 v[140:143], v[100:103], v[164:167], v[140:143]
	v_mfma_f32_16x16x32_bf16 v[136:139], v[116:119], v[164:167], v[136:139]
	v_mfma_f32_16x16x32_bf16 v[124:127], v[100:103], v[172:175], v[124:127]
	v_mfma_f32_16x16x32_bf16 v[120:123], v[116:119], v[172:175], v[120:123]
	v_mfma_f32_16x16x32_bf16 v[92:95], v[100:103], v[180:183], v[92:95]
	v_mfma_f32_16x16x32_bf16 v[88:91], v[116:119], v[180:183], v[88:91]
	v_mfma_f32_16x16x32_bf16 v[76:79], v[100:103], v[204:207], v[76:79]
	v_mfma_f32_16x16x32_bf16 v[72:75], v[116:119], v[204:207], v[72:75]
	v_mfma_f32_16x16x32_bf16 v[132:135], v[144:147], v[160:163], v[132:135]
	v_mfma_f32_16x16x32_bf16 v[128:131], v[152:155], v[160:163], v[128:131]
	v_mfma_f32_16x16x32_bf16 v[108:111], v[144:147], v[168:171], v[108:111]
	v_mfma_f32_16x16x32_bf16 v[104:107], v[152:155], v[168:171], v[104:107]
	v_mfma_f32_16x16x32_bf16 v[84:87], v[144:147], v[176:179], v[84:87]
	v_mfma_f32_16x16x32_bf16 v[80:83], v[152:155], v[176:179], v[80:83]
	v_mfma_f32_16x16x32_bf16 v[68:71], v[144:147], v[200:203], v[68:71]
	v_mfma_f32_16x16x32_bf16 v[64:67], v[152:155], v[200:203], v[64:67]
	v_mfma_f32_16x16x32_bf16 v[132:135], v[148:151], v[164:167], v[132:135]
	v_mfma_f32_16x16x32_bf16 v[128:131], v[156:159], v[164:167], v[128:131]
	v_mfma_f32_16x16x32_bf16 v[108:111], v[148:151], v[172:175], v[108:111]
	v_mfma_f32_16x16x32_bf16 v[104:107], v[156:159], v[172:175], v[104:107]
	v_mfma_f32_16x16x32_bf16 v[84:87], v[148:151], v[180:183], v[84:87]
	v_mfma_f32_16x16x32_bf16 v[80:83], v[156:159], v[180:183], v[80:83]
	v_mfma_f32_16x16x32_bf16 v[68:71], v[148:151], v[204:207], v[68:71]
	v_mfma_f32_16x16x32_bf16 v[64:67], v[156:159], v[204:207], v[64:67]
	s_barrier
; #define PG8_STAGE(bufoff, gbase, voff) do { _Pragma("unroll") for (int _i = 0; _i < 2; ++_i) \
;         __builtin_amdgcn_global_load_lds((const unsigned*)((const char*)(gbase) + (voff)[_i]), (LAS unsigned*)(lds + (bufoff) + ldsw + _i * 8192), 16, 0, 0); } while (0)
; #define PG8_LDA(dst, b, h) do { _Pragma("unroll") for (int m = 0; m < 4; ++m) _Pragma("unroll") for (int k = 0; k < 2; ++k) dst[m][k] = *(const LAS bf16x8*)(lds + PG8_SA(b, h) + aoff + m * 2048 + k * 1024); } while (0)
; #define PG8_MMA(ai, bj, At, Bt) do { __builtin_amdgcn_s_setprio(1); _Pragma("unroll") for (int m = 0; m < 4; ++m) _Pragma("unroll") for (int n = 0; n < 2; ++n) _Pragma("unroll") for (int k = 0; k < 2; ++k) \
;         acc[ai][bj][m][n] = __builtin_amdgcn_mfma_f32_16x16x32_bf16(Bt[n][k], At[m][k], acc[ai][bj][m][n], 0, 0, 0); __builtin_amdgcn_s_setprio(0); } while (0)
; #define PG8_WAIT_V(n) asm volatile("s_waitcnt vmcnt(" #n ")" ::: "memory")
; #define PG8_WAIT_L(n) asm volatile("s_waitcnt lgkmcnt(" #n ")" ::: "memory")
; #define PG8_BAR __builtin_amdgcn_s_barrier()
; #define PG8_SCHED __builtin_amdgcn_sched_barrier(0)
; template <class Epi, class Sched = StaticOrder, class EpiSub = NoSub, bool FAST = false>
; __device__ __forceinline__ void gemm_phase(LAS unsigned char* lds, const Gemm g, const Sched& S, const Epi& E, const EpiSub& ES = EpiSub()) {
;     ...
;             PG8_LDA(At, 1, 1); PG8_STAGE(PG8_SB(1, 0), b3, voffB); PG8_STAGE(PG8_SB(1, 1), b3 + hstepB, voffB); PG8_STAGE(PG8_SA(1, 0), a3, voffA);
;             PG8_WAIT_V(8); PG8_WAIT_L(0); PG8_BAR; PG8_MMA(1, 0, At, B0); PG8_MMA(1, 1, At, B1); PG8_BAR; PG8_SCHED;
;     ...
;         if constexpr (FAST && PG8_ALIGN) { if (wr == 0) PG8_BAR; }
	s_setprio 0
	s_add_i32 s42, s73, s17
	v_lshl_add_u64 v[208:209], v[208:209], 0, s[12:13]
	s_mov_b32 m0, s42
	ds_read_b128 v[160:163], v217 offset:49152
	ds_read_b128 v[164:167], v217 offset:50176
	ds_read_b128 v[168:171], v217 offset:51200
	ds_read_b128 v[172:175], v217 offset:52224
	ds_read_b128 v[176:179], v217 offset:53248
	ds_read_b128 v[180:183], v217 offset:54272
	ds_read_b128 v[200:203], v217 offset:55296
	ds_read_b128 v[204:207], v217 offset:56320
	global_load_lds_dwordx4 v[208:209], off
	s_add_i32 m0, s42, 0x2000
	s_add_u32 s40, s40, 0x80080
	v_lshl_add_u64 v[208:209], v[210:211], 0, s[12:13]
	s_addc_u32 s41, s41, 0
	s_add_i32 s42, s76, s17
	global_load_lds_dwordx4 v[208:209], off
	s_mov_b32 m0, s42
	v_lshl_add_u64 v[208:209], s[40:41], 0, v[186:187]
	global_load_lds_dwordx4 v[208:209], off
	s_add_i32 m0, s42, 0x2000
	v_lshl_add_u64 v[208:209], s[40:41], 0, v[190:191]
	global_load_lds_dwordx4 v[208:209], off
	s_mov_b32 m0, s55
	v_lshl_add_u64 v[208:209], v[218:219], 0, s[12:13]
	global_load_lds_dwordx4 v[208:209], off
	s_mov_b32 m0, s56
	v_lshl_add_u64 v[208:209], v[220:221], 0, s[12:13]
	global_load_lds_dwordx4 v[208:209], off
	s_waitcnt vmcnt(8)
	s_waitcnt lgkmcnt(0)
	s_setprio 1
	s_barrier
	v_mfma_f32_16x16x32_bf16 v[60:63], v[96:99], v[160:163], v[60:63]
	v_mfma_f32_16x16x32_bf16 v[56:59], v[112:115], v[160:163], v[56:59]
	v_mfma_f32_16x16x32_bf16 v[44:47], v[96:99], v[168:171], v[44:47]
	v_mfma_f32_16x16x32_bf16 v[40:43], v[112:115], v[168:171], v[40:43]
	v_mfma_f32_16x16x32_bf16 v[28:31], v[96:99], v[176:179], v[28:31]
	v_mfma_f32_16x16x32_bf16 v[24:27], v[112:115], v[176:179], v[24:27]
	v_mfma_f32_16x16x32_bf16 v[12:15], v[96:99], v[200:203], v[12:15]
	v_mfma_f32_16x16x32_bf16 v[8:11], v[112:115], v[200:203], v[8:11]
	v_mfma_f32_16x16x32_bf16 v[60:63], v[100:103], v[164:167], v[60:63]
	v_mfma_f32_16x16x32_bf16 v[56:59], v[116:119], v[164:167], v[56:59]
	v_mfma_f32_16x16x32_bf16 v[44:47], v[100:103], v[172:175], v[44:47]
	v_mfma_f32_16x16x32_bf16 v[40:43], v[116:119], v[172:175], v[40:43]
	v_mfma_f32_16x16x32_bf16 v[28:31], v[100:103], v[180:183], v[28:31]
	v_mfma_f32_16x16x32_bf16 v[24:27], v[116:119], v[180:183], v[24:27]
	v_mfma_f32_16x16x32_bf16 v[12:15], v[100:103], v[204:207], v[12:15]
	v_mfma_f32_16x16x32_bf16 v[8:11], v[116:119], v[204:207], v[8:11]
	v_mfma_f32_16x16x32_bf16 v[52:55], v[144:147], v[160:163], v[52:55]
	v_mfma_f32_16x16x32_bf16 v[48:51], v[152:155], v[160:163], v[48:51]
	v_mfma_f32_16x16x32_bf16 v[36:39], v[144:147], v[168:171], v[36:39]
	v_mfma_f32_16x16x32_bf16 v[32:35], v[152:155], v[168:171], v[32:35]
	v_mfma_f32_16x16x32_bf16 v[20:23], v[144:147], v[176:179], v[20:23]
	v_mfma_f32_16x16x32_bf16 v[16:19], v[152:155], v[176:179], v[16:19]
	v_mfma_f32_16x16x32_bf16 v[4:7], v[144:147], v[200:203], v[4:7]
	v_mfma_f32_16x16x32_bf16 v[0:3], v[152:155], v[200:203], v[0:3]
	v_mfma_f32_16x16x32_bf16 v[52:55], v[148:151], v[164:167], v[52:55]
	v_mfma_f32_16x16x32_bf16 v[48:51], v[156:159], v[164:167], v[48:51]
	v_mfma_f32_16x16x32_bf16 v[36:39], v[148:151], v[172:175], v[36:39]
	v_mfma_f32_16x16x32_bf16 v[32:35], v[156:159], v[172:175], v[32:35]
	v_mfma_f32_16x16x32_bf16 v[20:23], v[148:151], v[180:183], v[20:23]
	v_mfma_f32_16x16x32_bf16 v[16:19], v[156:159], v[180:183], v[16:19]
	v_mfma_f32_16x16x32_bf16 v[4:7], v[148:151], v[204:207], v[4:7]
	v_mfma_f32_16x16x32_bf16 v[0:3], v[156:159], v[204:207], v[0:3]
	s_barrier
	s_setprio 0
	s_add_u32 s38, s38, 0x100
	s_addc_u32 s39, s39, 0
	s_add_u32 s70, s70, 0x100
	s_addc_u32 s71, s71, 0
	s_cmp_ge_u32 s72, s29
	s_mov_b32 s42, s72
	s_cbranch_scc0 .LBB0_769
	s_and_b64 vcc, exec, s[14:15]
	s_cbranch_vccz .LBB0_772
	s_barrier

; #define PG8_STAGE(bufoff, gbase, voff) do { _Pragma("unroll") for (int _i = 0; _i < 2; ++_i) \
;         __builtin_amdgcn_global_load_lds((const unsigned*)((const char*)(gbase) + (voff)[_i]), (LAS unsigned*)(lds + (bufoff) + ldsw + _i * 8192), 16, 0, 0); } while (0)
; #define PG8_LDA(dst, b, h) do { _Pragma("unroll") for (int m = 0; m < 4; ++m) _Pragma("unroll") for (int k = 0; k < 2; ++k) dst[m][k] = *(const LAS bf16x8*)(lds + PG8_SA(b, h) + aoff + m * 2048 + k * 1024); } while (0)
; #define PG8_LDB(dst, b, h) do { _Pragma("unroll") for (int n = 0; n < 2; ++n) _Pragma("unroll") for (int k = 0; k < 2; ++k) dst[n][k] = *(const LAS bf16x8*)(lds + PG8_SB(b, h) + boff + n * 2048 + k * 1024); } while (0)
; #define PG8_MMA(ai, bj, At, Bt) do { __builtin_amdgcn_s_setprio(1); _Pragma("unroll") for (int m = 0; m < 4; ++m) _Pragma("unroll") for (int n = 0; n < 2; ++n) _Pragma("unroll") for (int k = 0; k < 2; ++k) \
;         acc[ai][bj][m][n] = __builtin_amdgcn_mfma_f32_16x16x32_bf16(Bt[n][k], At[m][k], acc[ai][bj][m][n], 0, 0, 0); __builtin_amdgcn_s_setprio(0); } while (0)
; #define PG8_WAIT_V(n) asm volatile("s_waitcnt vmcnt(" #n ")" ::: "memory")
; #define PG8_WAIT_L(n) asm volatile("s_waitcnt lgkmcnt(" #n ")" ::: "memory")
; #define PG8_BAR __builtin_amdgcn_s_barrier()
; #define PG8_SCHED __builtin_amdgcn_sched_barrier(0)
; template <class Epi, class Sched = StaticOrder, class EpiSub = NoSub, bool FAST = false>
; __device__ __forceinline__ void gemm_phase(LAS unsigned char* lds, const Gemm g, const Sched& S, const Epi& E, const EpiSub& ES = EpiSub()) {
;     ...
;         for (int t = 0; t < nt; t += 2) {
;             const bool last = (t == nt - 2);
;             const char* a1 = cA + (size_t)(t + 1) * kstep;
;             const char* a2 = last ? nA : cA + (size_t)(t + 2) * kstep; const char* b2 = last ? nB : cB + (size_t)(t + 2) * kstep;
;             const char* a3 = a2 + kstep; const char* b3 = b2 + kstep;
;             if constexpr (FAST && PG8_SP2) {
;             PG8_LDB(B0, 0, 0); PG8_LDB(B1, 0, 1); PG8_SCHED; PG8_LDA(At, 0, 0); PG8_STAGE(PG8_SA(1, 1), a1 + hstepA, voffA);
;             PG8_WAIT_V(8); PG8_WAIT_L(0); PG8_BAR; PG8_MMA(0, 0, At, B0); PG8_MMA(0, 1, At, B1); PG8_BAR; PG8_SCHED;
;             PG8_LDA(At, 0, 1); PG8_STAGE(PG8_SB(0, 0), b2, voffB); PG8_STAGE(PG8_SB(0, 1), b2 + hstepB, voffB); PG8_STAGE(PG8_SA(0, 0), a2, voffA);
.LBB0_985:
	ds_read_b128 v[150:153], v147
	ds_read_b128 v[154:157], v147 offset:1024
	ds_read_b128 v[158:161], v147 offset:2048
	ds_read_b128 v[162:165], v147 offset:3072
	ds_read_b128 v[166:169], v148
	ds_read_b128 v[170:173], v148 offset:1024
	ds_read_b128 v[174:177], v148 offset:2048
	ds_read_b128 v[178:181], v148 offset:3072
	s_add_u32 s24, s22, 0xfff80080
	s_addc_u32 s25, s23, -1
	s_cmp_eq_u32 s49, 28
	s_cselect_b32 s27, s15, s25
	s_cselect_b32 s26, s45, s24
	s_cselect_b32 s25, s13, s48
	s_cselect_b32 s24, s46, s47
	v_lshl_add_u64 v[190:191], s[22:23], 0, v[136:137]
	s_add_i32 m0, s21, 0xc000
	ds_read_b128 v[182:185], v149
	ds_read_b128 v[186:189], v149 offset:1024
	ds_read_b128 v[194:197], v149 offset:2048
	ds_read_b128 v[198:201], v149 offset:3072
	ds_read_b128 v[202:205], v149 offset:4096
	ds_read_b128 v[206:209], v149 offset:5120
	ds_read_b128 v[210:213], v149 offset:6144
	ds_read_b128 v[214:217], v149 offset:7168
	global_load_lds_dwordx4 v[190:191], off
	s_add_i32 m0, s21, 0xe000
	v_lshl_add_u64 v[190:191], s[22:23], 0, v[138:139]
	global_load_lds_dwordx4 v[190:191], off
	s_waitcnt vmcnt(8)
	s_waitcnt lgkmcnt(0)
	s_setprio 1
	s_barrier
	v_mfma_f32_16x16x32_bf16 v[124:127], v[150:153], v[182:185], v[124:127]
	v_mfma_f32_16x16x32_bf16 v[116:119], v[158:161], v[182:185], v[116:119]
	v_mfma_f32_16x16x32_bf16 v[108:111], v[150:153], v[194:197], v[108:111]
	v_mfma_f32_16x16x32_bf16 v[100:103], v[158:161], v[194:197], v[100:103]
	v_mfma_f32_16x16x32_bf16 v[92:95], v[150:153], v[202:205], v[92:95]
	v_mfma_f32_16x16x32_bf16 v[84:87], v[158:161], v[202:205], v[84:87]
	v_mfma_f32_16x16x32_bf16 v[76:79], v[150:153], v[210:213], v[76:79]
	v_mfma_f32_16x16x32_bf16 v[68:71], v[158:161], v[210:213], v[68:71]
	v_mfma_f32_16x16x32_bf16 v[124:127], v[154:157], v[186:189], v[124:127]
	v_mfma_f32_16x16x32_bf16 v[116:119], v[162:165], v[186:189], v[116:119]
	v_mfma_f32_16x16x32_bf16 v[108:111], v[154:157], v[198:201], v[108:111]
	v_mfma_f32_16x16x32_bf16 v[100:103], v[162:165], v[198:201], v[100:103]
	v_mfma_f32_16x16x32_bf16 v[92:95], v[154:157], v[206:209], v[92:95]
	v_mfma_f32_16x16x32_bf16 v[84:87], v[162:165], v[206:209], v[84:87]
	v_mfma_f32_16x16x32_bf16 v[76:79], v[154:157], v[214:217], v[76:79]
	v_mfma_f32_16x16x32_bf16 v[68:71], v[162:165], v[214:217], v[68:71]
	v_mfma_f32_16x16x32_bf16 v[120:123], v[166:169], v[182:185], v[120:123]
	v_mfma_f32_16x16x32_bf16 v[112:115], v[174:177], v[182:185], v[112:115]
	v_mfma_f32_16x16x32_bf16 v[104:107], v[166:169], v[194:197], v[104:107]
	v_mfma_f32_16x16x32_bf16 v[96:99], v[174:177], v[194:197], v[96:99]
	v_mfma_f32_16x16x32_bf16 v[88:91], v[166:169], v[202:205], v[88:91]
	v_mfma_f32_16x16x32_bf16 v[80:83], v[174:177], v[202:205], v[80:83]
	v_mfma_f32_16x16x32_bf16 v[72:75], v[166:169], v[210:213], v[72:75]
	v_mfma_f32_16x16x32_bf16 v[64:67], v[174:177], v[210:213], v[64:67]
	v_mfma_f32_16x16x32_bf16 v[120:123], v[170:173], v[186:189], v[120:123]
	v_mfma_f32_16x16x32_bf16 v[112:115], v[178:181], v[186:189], v[112:115]
	v_mfma_f32_16x16x32_bf16 v[104:107], v[170:173], v[198:201], v[104:107]
	v_mfma_f32_16x16x32_bf16 v[96:99], v[178:181], v[198:201], v[96:99]
	v_mfma_f32_16x16x32_bf16 v[88:91], v[170:173], v[206:209], v[88:91]
	v_mfma_f32_16x16x32_bf16 v[80:83], v[178:181], v[206:209], v[80:83]
	v_mfma_f32_16x16x32_bf16 v[72:75], v[170:173], v[214:217], v[72:75]
	v_mfma_f32_16x16x32_bf16 v[64:67], v[178:181], v[214:217], v[64:67]
	s_barrier
	s_setprio 0
	s_add_i32 s50, s42, s28
	v_lshl_add_u64 v[190:191], s[24:25], 0, v[130:131]
	s_mov_b32 m0, s50
	ds_read_b128 v[182:185], v149 offset:16384
	ds_read_b128 v[186:189], v149 offset:17408
	ds_read_b128 v[194:197], v149 offset:18432
	ds_read_b128 v[198:201], v149 offset:19456
	ds_read_b128 v[202:205], v149 offset:20480
	ds_read_b128 v[206:209], v149 offset:21504
	ds_read_b128 v[210:213], v149 offset:22528
	ds_read_b128 v[214:217], v149 offset:23552
	global_load_lds_dwordx4 v[190:191], off
	s_add_i32 m0, s50, 0x2000
	s_add_u32 s50, s24, 0x80000
	v_lshl_add_u64 v[218:219], s[24:25], 0, v[134:135]
	s_addc_u32 s51, s25, 0
	s_add_i32 s52, s43, s28
	global_load_lds_dwordx4 v[218:219], off
	v_lshl_add_u64 v[220:221], s[50:51], 0, v[130:131]
	s_mov_b32 m0, s52
	v_lshl_add_u64 v[222:223], s[26:27], 0, v[132:133]
	global_load_lds_dwordx4 v[220:221], off
	s_add_i32 m0, s52, 0x2000
	v_lshl_add_u64 v[220:221], s[50:51], 0, v[134:135]
	global_load_lds_dwordx4 v[220:221], off
	s_mov_b32 m0, s21
	v_lshl_add_u64 v[220:221], s[26:27], 0, v[128:129]
	global_load_lds_dwordx4 v[220:221], off
	s_mov_b32 m0, s31
	s_nop 0
	global_load_lds_dwordx4 v[222:223], off
	s_waitcnt vmcnt(8)
	s_waitcnt lgkmcnt(0)
	s_setprio 1
	s_barrier
; #define PG8_STAGE(bufoff, gbase, voff) do { _Pragma("unroll") for (int _i = 0; _i < 2; ++_i) \
;         __builtin_amdgcn_global_load_lds((const unsigned*)((const char*)(gbase) + (voff)[_i]), (LAS unsigned*)(lds + (bufoff) + ldsw + _i * 8192), 16, 0, 0); } while (0)
; #define PG8_LDA(dst, b, h) do { _Pragma("unroll") for (int m = 0; m < 4; ++m) _Pragma("unroll") for (int k = 0; k < 2; ++k) dst[m][k] = *(const LAS bf16x8*)(lds + PG8_SA(b, h) + aoff + m * 2048 + k * 1024); } while (0)
; #define PG8_LDB(dst, b, h) do { _Pragma("unroll") for (int n = 0; n < 2; ++n) _Pragma("unroll") for (int k = 0; k < 2; ++k) dst[n][k] = *(const LAS bf16x8*)(lds + PG8_SB(b, h) + boff + n * 2048 + k * 1024); } while (0)
; #define PG8_MMA(ai, bj, At, Bt) do { __builtin_amdgcn_s_setprio(1); _Pragma("unroll") for (int m = 0; m < 4; ++m) _Pragma("unroll") for (int n = 0; n < 2; ++n) _Pragma("unroll") for (int k = 0; k < 2; ++k) \
;         acc[ai][bj][m][n] = __builtin_amdgcn_mfma_f32_16x16x32_bf16(Bt[n][k], At[m][k], acc[ai][bj][m][n], 0, 0, 0); __builtin_amdgcn_s_setprio(0); } while (0)
; #define PG8_WAIT_V(n) asm volatile("s_waitcnt vmcnt(" #n ")" ::: "memory")
; #define PG8_WAIT_L(n) asm volatile("s_waitcnt lgkmcnt(" #n ")" ::: "memory")
; #define PG8_BAR __builtin_amdgcn_s_barrier()
; #define PG8_SCHED __builtin_amdgcn_sched_barrier(0)
; template <class Epi, class Sched = StaticOrder, class EpiSub = NoSub, bool FAST = false>
; __device__ __forceinline__ void gemm_phase(LAS unsigned char* lds, const Gemm g, const Sched& S, const Epi& E, const EpiSub& ES = EpiSub()) {
;     ...
;             PG8_WAIT_V(8); PG8_WAIT_L(0); PG8_BAR; PG8_MMA(1, 0, At, B0); PG8_MMA(1, 1, At, B1); PG8_BAR; PG8_SCHED;
;             PG8_LDB(B0, 1, 0); PG8_LDB(B1, 1, 1); PG8_SCHED; PG8_LDA(At, 1, 0); PG8_STAGE(PG8_SA(0, 1), a2 + hstepA, voffA);
;             PG8_WAIT_V(8); PG8_WAIT_L(0); PG8_BAR; PG8_MMA(0, 0, At, B0); PG8_MMA(0, 1, At, B1); PG8_BAR; PG8_SCHED;
	v_mfma_f32_16x16x32_bf16 v[60:63], v[150:153], v[182:185], v[60:63]
	v_mfma_f32_16x16x32_bf16 v[52:55], v[158:161], v[182:185], v[52:55]
	v_mfma_f32_16x16x32_bf16 v[44:47], v[150:153], v[194:197], v[44:47]
	v_mfma_f32_16x16x32_bf16 v[36:39], v[158:161], v[194:197], v[36:39]
	v_mfma_f32_16x16x32_bf16 v[28:31], v[150:153], v[202:205], v[28:31]
	v_mfma_f32_16x16x32_bf16 v[20:23], v[158:161], v[202:205], v[20:23]
	v_mfma_f32_16x16x32_bf16 v[12:15], v[150:153], v[210:213], v[12:15]
	v_mfma_f32_16x16x32_bf16 v[4:7], v[158:161], v[210:213], v[4:7]
	v_mfma_f32_16x16x32_bf16 v[60:63], v[154:157], v[186:189], v[60:63]
	v_mfma_f32_16x16x32_bf16 v[52:55], v[162:165], v[186:189], v[52:55]
	v_mfma_f32_16x16x32_bf16 v[44:47], v[154:157], v[198:201], v[44:47]
	v_mfma_f32_16x16x32_bf16 v[36:39], v[162:165], v[198:201], v[36:39]
	v_mfma_f32_16x16x32_bf16 v[28:31], v[154:157], v[206:209], v[28:31]
	v_mfma_f32_16x16x32_bf16 v[20:23], v[162:165], v[206:209], v[20:23]
	v_mfma_f32_16x16x32_bf16 v[12:15], v[154:157], v[214:217], v[12:15]
	v_mfma_f32_16x16x32_bf16 v[4:7], v[162:165], v[214:217], v[4:7]
	v_mfma_f32_16x16x32_bf16 v[56:59], v[166:169], v[182:185], v[56:59]
	v_mfma_f32_16x16x32_bf16 v[48:51], v[174:177], v[182:185], v[48:51]
	v_mfma_f32_16x16x32_bf16 v[40:43], v[166:169], v[194:197], v[40:43]
	v_mfma_f32_16x16x32_bf16 v[32:35], v[174:177], v[194:197], v[32:35]
	v_mfma_f32_16x16x32_bf16 v[24:27], v[166:169], v[202:205], v[24:27]
	v_mfma_f32_16x16x32_bf16 v[16:19], v[174:177], v[202:205], v[16:19]
	v_mfma_f32_16x16x32_bf16 v[8:11], v[166:169], v[210:213], v[8:11]
	v_mfma_f32_16x16x32_bf16 v[0:3], v[174:177], v[210:213], v[0:3]
	v_mfma_f32_16x16x32_bf16 v[56:59], v[170:173], v[186:189], v[56:59]
	v_mfma_f32_16x16x32_bf16 v[48:51], v[178:181], v[186:189], v[48:51]
	v_mfma_f32_16x16x32_bf16 v[40:43], v[170:173], v[198:201], v[40:43]
	v_mfma_f32_16x16x32_bf16 v[32:35], v[178:181], v[198:201], v[32:35]
	v_mfma_f32_16x16x32_bf16 v[24:27], v[170:173], v[206:209], v[24:27]
	v_mfma_f32_16x16x32_bf16 v[16:19], v[178:181], v[206:209], v[16:19]
	v_mfma_f32_16x16x32_bf16 v[8:11], v[170:173], v[214:217], v[8:11]
	v_mfma_f32_16x16x32_bf16 v[0:3], v[178:181], v[214:217], v[0:3]
	s_barrier
	s_setprio 0
	s_add_i32 s50, 0, 0x18000
	s_add_i32 s51, 0, 0x1c000
	v_add_u32_e32 v162, s50, v145
	v_add_u32_e32 v178, s51, v145
	ds_read_b128 v[150:153], v162
	ds_read_b128 v[154:157], v162 offset:1024
	ds_read_b128 v[158:161], v162 offset:2048
	ds_read_b128 v[162:165], v162 offset:3072
	ds_read_b128 v[166:169], v178
	ds_read_b128 v[170:173], v178 offset:1024
	ds_read_b128 v[174:177], v178 offset:2048
	ds_read_b128 v[178:181], v178 offset:3072
	s_add_u32 s26, s26, 0x80000
	s_addc_u32 s27, s27, 0
	s_mov_b32 m0, s36
	v_lshl_add_u64 v[224:225], s[26:27], 0, v[128:129]
	ds_read_b128 v[182:185], v149 offset:32768
	ds_read_b128 v[186:189], v149 offset:33792
	ds_read_b128 v[194:197], v149 offset:34816
	ds_read_b128 v[198:201], v149 offset:35840
	ds_read_b128 v[202:205], v149 offset:36864
	ds_read_b128 v[206:209], v149 offset:37888
	ds_read_b128 v[210:213], v149 offset:38912
	ds_read_b128 v[214:217], v149 offset:39936
	global_load_lds_dwordx4 v[224:225], off
	s_mov_b32 m0, s37
	v_lshl_add_u64 v[224:225], s[26:27], 0, v[132:133]
	global_load_lds_dwordx4 v[224:225], off
	s_waitcnt vmcnt(8)
	s_waitcnt lgkmcnt(0)
	s_setprio 1
	s_barrier
	v_mfma_f32_16x16x32_bf16 v[124:127], v[150:153], v[182:185], v[124:127]
	v_mfma_f32_16x16x32_bf16 v[116:119], v[158:161], v[182:185], v[116:119]
	v_mfma_f32_16x16x32_bf16 v[108:111], v[150:153], v[194:197], v[108:111]
	v_mfma_f32_16x16x32_bf16 v[100:103], v[158:161], v[194:197], v[100:103]
	v_mfma_f32_16x16x32_bf16 v[92:95], v[150:153], v[202:205], v[92:95]
	v_mfma_f32_16x16x32_bf16 v[84:87], v[158:161], v[202:205], v[84:87]
	v_mfma_f32_16x16x32_bf16 v[76:79], v[150:153], v[210:213], v[76:79]
	v_mfma_f32_16x16x32_bf16 v[68:71], v[158:161], v[210:213], v[68:71]
	v_mfma_f32_16x16x32_bf16 v[124:127], v[154:157], v[186:189], v[124:127]
	v_mfma_f32_16x16x32_bf16 v[116:119], v[162:165], v[186:189], v[116:119]
	v_mfma_f32_16x16x32_bf16 v[108:111], v[154:157], v[198:201], v[108:111]
	v_mfma_f32_16x16x32_bf16 v[100:103], v[162:165], v[198:201], v[100:103]
	v_mfma_f32_16x16x32_bf16 v[92:95], v[154:157], v[206:209], v[92:95]
	v_mfma_f32_16x16x32_bf16 v[84:87], v[162:165], v[206:209], v[84:87]
	v_mfma_f32_16x16x32_bf16 v[76:79], v[154:157], v[214:217], v[76:79]
	v_mfma_f32_16x16x32_bf16 v[68:71], v[162:165], v[214:217], v[68:71]
	v_mfma_f32_16x16x32_bf16 v[120:123], v[166:169], v[182:185], v[120:123]
	v_mfma_f32_16x16x32_bf16 v[112:115], v[174:177], v[182:185], v[112:115]
	v_mfma_f32_16x16x32_bf16 v[104:107], v[166:169], v[194:197], v[104:107]
	v_mfma_f32_16x16x32_bf16 v[96:99], v[174:177], v[194:197], v[96:99]
	v_mfma_f32_16x16x32_bf16 v[88:91], v[166:169], v[202:205], v[88:91]
	v_mfma_f32_16x16x32_bf16 v[80:83], v[174:177], v[202:205], v[80:83]
	v_mfma_f32_16x16x32_bf16 v[72:75], v[166:169], v[210:213], v[72:75]
	v_mfma_f32_16x16x32_bf16 v[64:67], v[174:177], v[210:213], v[64:67]
	v_mfma_f32_16x16x32_bf16 v[120:123], v[170:173], v[186:189], v[120:123]
	v_mfma_f32_16x16x32_bf16 v[112:115], v[178:181], v[186:189], v[112:115]
	v_mfma_f32_16x16x32_bf16 v[104:107], v[170:173], v[198:201], v[104:107]
	v_mfma_f32_16x16x32_bf16 v[96:99], v[178:181], v[198:201], v[96:99]
	v_mfma_f32_16x16x32_bf16 v[88:91], v[170:173], v[206:209], v[88:91]
	v_mfma_f32_16x16x32_bf16 v[80:83], v[178:181], v[206:209], v[80:83]
	v_mfma_f32_16x16x32_bf16 v[72:75], v[170:173], v[214:217], v[72:75]
	v_mfma_f32_16x16x32_bf16 v[64:67], v[178:181], v[214:217], v[64:67]
	s_barrier
; #define PG8_STAGE(bufoff, gbase, voff) do { _Pragma("unroll") for (int _i = 0; _i < 2; ++_i) \
;         __builtin_amdgcn_global_load_lds((const unsigned*)((const char*)(gbase) + (voff)[_i]), (LAS unsigned*)(lds + (bufoff) + ldsw + _i * 8192), 16, 0, 0); } while (0)
; #define PG8_LDA(dst, b, h) do { _Pragma("unroll") for (int m = 0; m < 4; ++m) _Pragma("unroll") for (int k = 0; k < 2; ++k) dst[m][k] = *(const LAS bf16x8*)(lds + PG8_SA(b, h) + aoff + m * 2048 + k * 1024); } while (0)
; #define PG8_MMA(ai, bj, At, Bt) do { __builtin_amdgcn_s_setprio(1); _Pragma("unroll") for (int m = 0; m < 4; ++m) _Pragma("unroll") for (int n = 0; n < 2; ++n) _Pragma("unroll") for (int k = 0; k < 2; ++k) \
;         acc[ai][bj][m][n] = __builtin_amdgcn_mfma_f32_16x16x32_bf16(Bt[n][k], At[m][k], acc[ai][bj][m][n], 0, 0, 0); __builtin_amdgcn_s_setprio(0); } while (0)
; #define PG8_WAIT_V(n) asm volatile("s_waitcnt vmcnt(" #n ")" ::: "memory")
; #define PG8_WAIT_L(n) asm volatile("s_waitcnt lgkmcnt(" #n ")" ::: "memory")
; #define PG8_BAR __builtin_amdgcn_s_barrier()
; #define PG8_SCHED __builtin_amdgcn_sched_barrier(0)
; template <class Epi, class Sched = StaticOrder, class EpiSub = NoSub, bool FAST = false>
; __device__ __forceinline__ void gemm_phase(LAS unsigned char* lds, const Gemm g, const Sched& S, const Epi& E, const EpiSub& ES = EpiSub()) {
;     ...
;             PG8_LDA(At, 1, 1); PG8_STAGE(PG8_SB(1, 0), b3, voffB); PG8_STAGE(PG8_SB(1, 1), b3 + hstepB, voffB); PG8_STAGE(PG8_SA(1, 0), a3, voffA);
;             PG8_WAIT_V(8); PG8_WAIT_L(0); PG8_BAR; PG8_MMA(1, 0, At, B0); PG8_MMA(1, 1, At, B1); PG8_BAR; PG8_SCHED;
;     ...
;         if constexpr (FAST && PG8_ALIGN) { if (wr == 0) PG8_BAR; }
	s_setprio 0
	s_add_i32 s26, s50, s28
	v_lshl_add_u64 v[190:191], v[190:191], 0, s[8:9]
	s_mov_b32 m0, s26
	ds_read_b128 v[182:185], v149 offset:49152
	ds_read_b128 v[186:189], v149 offset:50176
	ds_read_b128 v[194:197], v149 offset:51200
	ds_read_b128 v[198:201], v149 offset:52224
	ds_read_b128 v[202:205], v149 offset:53248
	ds_read_b128 v[206:209], v149 offset:54272
	ds_read_b128 v[210:213], v149 offset:55296
	ds_read_b128 v[214:217], v149 offset:56320
	global_load_lds_dwordx4 v[190:191], off
	s_add_i32 m0, s26, 0x2000
	s_add_u32 s24, s24, 0x80080
	v_lshl_add_u64 v[190:191], v[218:219], 0, s[8:9]
	s_addc_u32 s25, s25, 0
	s_add_i32 s26, s51, s28
	global_load_lds_dwordx4 v[190:191], off
	s_mov_b32 m0, s26
	v_lshl_add_u64 v[190:191], s[24:25], 0, v[130:131]
	global_load_lds_dwordx4 v[190:191], off
	s_add_i32 m0, s26, 0x2000
	v_lshl_add_u64 v[190:191], s[24:25], 0, v[134:135]
	global_load_lds_dwordx4 v[190:191], off
	s_mov_b32 m0, s40
	v_lshl_add_u64 v[190:191], v[220:221], 0, s[8:9]
	global_load_lds_dwordx4 v[190:191], off
	s_mov_b32 m0, s41
	v_lshl_add_u64 v[190:191], v[222:223], 0, s[8:9]
	global_load_lds_dwordx4 v[190:191], off
	s_waitcnt vmcnt(8)
	s_waitcnt lgkmcnt(0)
	s_setprio 1
	s_barrier
	v_mfma_f32_16x16x32_bf16 v[60:63], v[150:153], v[182:185], v[60:63]
	v_mfma_f32_16x16x32_bf16 v[52:55], v[158:161], v[182:185], v[52:55]
	v_mfma_f32_16x16x32_bf16 v[44:47], v[150:153], v[194:197], v[44:47]
	v_mfma_f32_16x16x32_bf16 v[36:39], v[158:161], v[194:197], v[36:39]
	v_mfma_f32_16x16x32_bf16 v[28:31], v[150:153], v[202:205], v[28:31]
	v_mfma_f32_16x16x32_bf16 v[20:23], v[158:161], v[202:205], v[20:23]
	v_mfma_f32_16x16x32_bf16 v[12:15], v[150:153], v[210:213], v[12:15]
	v_mfma_f32_16x16x32_bf16 v[4:7], v[158:161], v[210:213], v[4:7]
	v_mfma_f32_16x16x32_bf16 v[60:63], v[154:157], v[186:189], v[60:63]
	v_mfma_f32_16x16x32_bf16 v[52:55], v[162:165], v[186:189], v[52:55]
	v_mfma_f32_16x16x32_bf16 v[44:47], v[154:157], v[198:201], v[44:47]
	v_mfma_f32_16x16x32_bf16 v[36:39], v[162:165], v[198:201], v[36:39]
	v_mfma_f32_16x16x32_bf16 v[28:31], v[154:157], v[206:209], v[28:31]
	v_mfma_f32_16x16x32_bf16 v[20:23], v[162:165], v[206:209], v[20:23]
	v_mfma_f32_16x16x32_bf16 v[12:15], v[154:157], v[214:217], v[12:15]
	v_mfma_f32_16x16x32_bf16 v[4:7], v[162:165], v[214:217], v[4:7]
	v_mfma_f32_16x16x32_bf16 v[56:59], v[166:169], v[182:185], v[56:59]
	v_mfma_f32_16x16x32_bf16 v[48:51], v[174:177], v[182:185], v[48:51]
	v_mfma_f32_16x16x32_bf16 v[40:43], v[166:169], v[194:197], v[40:43]
	v_mfma_f32_16x16x32_bf16 v[32:35], v[174:177], v[194:197], v[32:35]
	v_mfma_f32_16x16x32_bf16 v[24:27], v[166:169], v[202:205], v[24:27]
	v_mfma_f32_16x16x32_bf16 v[16:19], v[174:177], v[202:205], v[16:19]
	v_mfma_f32_16x16x32_bf16 v[8:11], v[166:169], v[210:213], v[8:11]
	v_mfma_f32_16x16x32_bf16 v[0:3], v[174:177], v[210:213], v[0:3]
	v_mfma_f32_16x16x32_bf16 v[56:59], v[170:173], v[186:189], v[56:59]
	v_mfma_f32_16x16x32_bf16 v[48:51], v[178:181], v[186:189], v[48:51]
	v_mfma_f32_16x16x32_bf16 v[40:43], v[170:173], v[198:201], v[40:43]
	v_mfma_f32_16x16x32_bf16 v[32:35], v[178:181], v[198:201], v[32:35]
	v_mfma_f32_16x16x32_bf16 v[24:27], v[170:173], v[206:209], v[24:27]
	v_mfma_f32_16x16x32_bf16 v[16:19], v[178:181], v[206:209], v[16:19]
	v_mfma_f32_16x16x32_bf16 v[8:11], v[170:173], v[214:217], v[8:11]
	v_mfma_f32_16x16x32_bf16 v[0:3], v[178:181], v[214:217], v[0:3]
	s_barrier
	s_setprio 0
	s_add_i32 s49, s49, 2
	s_add_u32 s22, s22, 0x100
	s_addc_u32 s23, s23, 0
	s_add_u32 s47, s47, 0x100
	s_addc_u32 s48, s48, 0
	s_cmp_gt_u32 s49, 29
	s_cbranch_scc0 .LBB0_985
	s_and_b64 vcc, exec, s[10:11]
	s_cbranch_vccz .LBB0_988
	s_barrier

; #define PG8_STAGE(bufoff, gbase, voff) do { _Pragma("unroll") for (int _i = 0; _i < 2; ++_i) \
;         __builtin_amdgcn_global_load_lds((const unsigned*)((const char*)(gbase) + (voff)[_i]), (LAS unsigned*)(lds + (bufoff) + ldsw + _i * 8192), 16, 0, 0); } while (0)
; #define PG8_LDA(dst, b, h) do { _Pragma("unroll") for (int m = 0; m < 4; ++m) _Pragma("unroll") for (int k = 0; k < 2; ++k) dst[m][k] = *(const LAS bf16x8*)(lds + PG8_SA(b, h) + aoff + m * 2048 + k * 1024); } while (0)
; #define PG8_LDB(dst, b, h) do { _Pragma("unroll") for (int n = 0; n < 2; ++n) _Pragma("unroll") for (int k = 0; k < 2; ++k) dst[n][k] = *(const LAS bf16x8*)(lds + PG8_SB(b, h) + boff + n * 2048 + k * 1024); } while (0)
; #define PG8_MMA(ai, bj, At, Bt) do { __builtin_amdgcn_s_setprio(1); _Pragma("unroll") for (int m = 0; m < 4; ++m) _Pragma("unroll") for (int n = 0; n < 2; ++n) _Pragma("unroll") for (int k = 0; k < 2; ++k) \
;         acc[ai][bj][m][n] = __builtin_amdgcn_mfma_f32_16x16x32_bf16(Bt[n][k], At[m][k], acc[ai][bj][m][n], 0, 0, 0); __builtin_amdgcn_s_setprio(0); } while (0)
; #define PG8_WAIT_V(n) asm volatile("s_waitcnt vmcnt(" #n ")" ::: "memory")
; #define PG8_WAIT_L(n) asm volatile("s_waitcnt lgkmcnt(" #n ")" ::: "memory")
; #define PG8_BAR __builtin_amdgcn_s_barrier()
; #define PG8_SCHED __builtin_amdgcn_sched_barrier(0)
; template <class Epi, class Sched = StaticOrder, class EpiSub = NoSub, bool FAST = false>
; __device__ __forceinline__ void gemm_phase(LAS unsigned char* lds, const Gemm g, const Sched& S, const Epi& E, const EpiSub& ES = EpiSub()) {
;     ...
;         for (int t = 0; t < nt; t += 2) {
;             const bool last = (t == nt - 2);
;             const char* a1 = cA + (size_t)(t + 1) * kstep;
;             const char* a2 = last ? nA : cA + (size_t)(t + 2) * kstep; const char* b2 = last ? nB : cB + (size_t)(t + 2) * kstep;
;             const char* a3 = a2 + kstep; const char* b3 = b2 + kstep;
;             if constexpr (FAST && PG8_SP2) {
;             PG8_LDB(B0, 0, 0); PG8_LDB(B1, 0, 1); PG8_SCHED; PG8_LDA(At, 0, 0); PG8_STAGE(PG8_SA(1, 1), a1 + hstepA, voffA);
;             PG8_WAIT_V(8); PG8_WAIT_L(0); PG8_BAR; PG8_MMA(0, 0, At, B0); PG8_MMA(0, 1, At, B1); PG8_BAR; PG8_SCHED;
;             PG8_LDA(At, 0, 1); PG8_STAGE(PG8_SB(0, 0), b2, voffB); PG8_STAGE(PG8_SB(0, 1), b2 + hstepB, voffB); PG8_STAGE(PG8_SA(0, 0), a2, voffA);
.LBB0_1079:
	ds_read_b128 v[96:99], v201
	ds_read_b128 v[100:103], v201 offset:1024
	ds_read_b128 v[108:111], v201 offset:2048
	ds_read_b128 v[116:119], v201 offset:3072
	ds_read_b128 v[144:147], v202
	ds_read_b128 v[148:151], v202 offset:1024
	ds_read_b128 v[152:155], v202 offset:2048
	ds_read_b128 v[156:159], v202 offset:3072
	s_add_i32 s85, s46, 2
	s_add_u32 s44, s42, 0xffea0080
	s_addc_u32 s45, s43, -1
	s_cmp_eq_u32 s71, s46
	s_cselect_b32 s46, s38, s44
	s_cselect_b32 s47, s39, s45
	s_cselect_b32 s45, s41, s84
	s_cselect_b32 s44, s40, s83
	v_lshl_add_u64 v[190:191], s[42:43], 0, v[176:177]
	s_add_i32 m0, s48, 0xc000
	ds_read_b128 v[160:163], v203
	ds_read_b128 v[164:167], v203 offset:1024
	ds_read_b128 v[182:185], v203 offset:2048
	ds_read_b128 v[186:189], v203 offset:3072
	ds_read_b128 v[194:197], v203 offset:4096
	ds_read_b128 v[204:207], v203 offset:5120
	ds_read_b128 v[208:211], v203 offset:6144
	ds_read_b128 v[212:215], v203 offset:7168
	global_load_lds_dwordx4 v[190:191], off
	s_add_i32 m0, s48, 0xe000
	v_lshl_add_u64 v[190:191], s[42:43], 0, v[178:179]
	global_load_lds_dwordx4 v[190:191], off
	s_waitcnt vmcnt(8)
	s_waitcnt lgkmcnt(0)
	s_setprio 1
	s_barrier
	v_mfma_f32_16x16x32_bf16 v[140:143], v[96:99], v[160:163], v[140:143]
	v_mfma_f32_16x16x32_bf16 v[136:139], v[108:111], v[160:163], v[136:139]
	v_mfma_f32_16x16x32_bf16 v[124:127], v[96:99], v[182:185], v[124:127]
	v_mfma_f32_16x16x32_bf16 v[120:123], v[108:111], v[182:185], v[120:123]
	v_mfma_f32_16x16x32_bf16 v[92:95], v[96:99], v[194:197], v[92:95]
	v_mfma_f32_16x16x32_bf16 v[88:91], v[108:111], v[194:197], v[88:91]
	v_mfma_f32_16x16x32_bf16 v[76:79], v[96:99], v[208:211], v[76:79]
	v_mfma_f32_16x16x32_bf16 v[72:75], v[108:111], v[208:211], v[72:75]
	v_mfma_f32_16x16x32_bf16 v[140:143], v[100:103], v[164:167], v[140:143]
	v_mfma_f32_16x16x32_bf16 v[136:139], v[116:119], v[164:167], v[136:139]
	v_mfma_f32_16x16x32_bf16 v[124:127], v[100:103], v[186:189], v[124:127]
	v_mfma_f32_16x16x32_bf16 v[120:123], v[116:119], v[186:189], v[120:123]
	v_mfma_f32_16x16x32_bf16 v[92:95], v[100:103], v[204:207], v[92:95]
	v_mfma_f32_16x16x32_bf16 v[88:91], v[116:119], v[204:207], v[88:91]
	v_mfma_f32_16x16x32_bf16 v[76:79], v[100:103], v[212:215], v[76:79]
	v_mfma_f32_16x16x32_bf16 v[72:75], v[116:119], v[212:215], v[72:75]
	v_mfma_f32_16x16x32_bf16 v[132:135], v[144:147], v[160:163], v[132:135]
	v_mfma_f32_16x16x32_bf16 v[128:131], v[152:155], v[160:163], v[128:131]
	v_mfma_f32_16x16x32_bf16 v[112:115], v[144:147], v[182:185], v[112:115]
	v_mfma_f32_16x16x32_bf16 v[104:107], v[152:155], v[182:185], v[104:107]
	v_mfma_f32_16x16x32_bf16 v[84:87], v[144:147], v[194:197], v[84:87]
	v_mfma_f32_16x16x32_bf16 v[80:83], v[152:155], v[194:197], v[80:83]
	v_mfma_f32_16x16x32_bf16 v[68:71], v[144:147], v[208:211], v[68:71]
	v_mfma_f32_16x16x32_bf16 v[64:67], v[152:155], v[208:211], v[64:67]
	v_mfma_f32_16x16x32_bf16 v[132:135], v[148:151], v[164:167], v[132:135]
	v_mfma_f32_16x16x32_bf16 v[128:131], v[156:159], v[164:167], v[128:131]
	v_mfma_f32_16x16x32_bf16 v[112:115], v[148:151], v[186:189], v[112:115]
	v_mfma_f32_16x16x32_bf16 v[104:107], v[156:159], v[186:189], v[104:107]
	v_mfma_f32_16x16x32_bf16 v[84:87], v[148:151], v[204:207], v[84:87]
	v_mfma_f32_16x16x32_bf16 v[80:83], v[156:159], v[204:207], v[80:83]
	v_mfma_f32_16x16x32_bf16 v[68:71], v[148:151], v[212:215], v[68:71]
	v_mfma_f32_16x16x32_bf16 v[64:67], v[156:159], v[212:215], v[64:67]
	s_barrier
	s_setprio 0
	s_add_i32 s86, s58, s27
	v_lshl_add_u64 v[190:191], s[44:45], 0, v[170:171]
	s_mov_b32 m0, s86
	ds_read_b128 v[160:163], v203 offset:16384
	ds_read_b128 v[164:167], v203 offset:17408
	ds_read_b128 v[182:185], v203 offset:18432
	ds_read_b128 v[186:189], v203 offset:19456
	ds_read_b128 v[194:197], v203 offset:20480
	ds_read_b128 v[204:207], v203 offset:21504
	ds_read_b128 v[208:211], v203 offset:22528
	ds_read_b128 v[212:215], v203 offset:23552
	global_load_lds_dwordx4 v[190:191], off
	s_add_i32 m0, s86, 0x2000
	s_add_u32 s86, s44, 0x160000
	v_lshl_add_u64 v[216:217], s[44:45], 0, v[174:175]
	s_addc_u32 s87, s45, 0
	s_add_i32 s88, s59, s27
	global_load_lds_dwordx4 v[216:217], off
	v_lshl_add_u64 v[218:219], s[86:87], 0, v[170:171]
	s_mov_b32 m0, s88
	v_lshl_add_u64 v[220:221], s[46:47], 0, v[172:173]
	global_load_lds_dwordx4 v[218:219], off
	s_add_i32 m0, s88, 0x2000
	v_lshl_add_u64 v[218:219], s[86:87], 0, v[174:175]
	global_load_lds_dwordx4 v[218:219], off
	s_mov_b32 m0, s48
	v_lshl_add_u64 v[218:219], s[46:47], 0, v[168:169]
	global_load_lds_dwordx4 v[218:219], off
	s_mov_b32 m0, s49
	s_nop 0
	global_load_lds_dwordx4 v[220:221], off
	s_waitcnt vmcnt(8)
	s_waitcnt lgkmcnt(0)
	s_setprio 1
	s_barrier
; #define PG8_STAGE(bufoff, gbase, voff) do { _Pragma("unroll") for (int _i = 0; _i < 2; ++_i) \
;         __builtin_amdgcn_global_load_lds((const unsigned*)((const char*)(gbase) + (voff)[_i]), (LAS unsigned*)(lds + (bufoff) + ldsw + _i * 8192), 16, 0, 0); } while (0)
; #define PG8_LDA(dst, b, h) do { _Pragma("unroll") for (int m = 0; m < 4; ++m) _Pragma("unroll") for (int k = 0; k < 2; ++k) dst[m][k] = *(const LAS bf16x8*)(lds + PG8_SA(b, h) + aoff + m * 2048 + k * 1024); } while (0)
; #define PG8_LDB(dst, b, h) do { _Pragma("unroll") for (int n = 0; n < 2; ++n) _Pragma("unroll") for (int k = 0; k < 2; ++k) dst[n][k] = *(const LAS bf16x8*)(lds + PG8_SB(b, h) + boff + n * 2048 + k * 1024); } while (0)
; #define PG8_MMA(ai, bj, At, Bt) do { __builtin_amdgcn_s_setprio(1); _Pragma("unroll") for (int m = 0; m < 4; ++m) _Pragma("unroll") for (int n = 0; n < 2; ++n) _Pragma("unroll") for (int k = 0; k < 2; ++k) \
;         acc[ai][bj][m][n] = __builtin_amdgcn_mfma_f32_16x16x32_bf16(Bt[n][k], At[m][k], acc[ai][bj][m][n], 0, 0, 0); __builtin_amdgcn_s_setprio(0); } while (0)
; #define PG8_WAIT_V(n) asm volatile("s_waitcnt vmcnt(" #n ")" ::: "memory")
; #define PG8_WAIT_L(n) asm volatile("s_waitcnt lgkmcnt(" #n ")" ::: "memory")
; #define PG8_BAR __builtin_amdgcn_s_barrier()
; #define PG8_SCHED __builtin_amdgcn_sched_barrier(0)
; template <class Epi, class Sched = StaticOrder, class EpiSub = NoSub, bool FAST = false>
; __device__ __forceinline__ void gemm_phase(LAS unsigned char* lds, const Gemm g, const Sched& S, const Epi& E, const EpiSub& ES = EpiSub()) {
;     ...
;             PG8_WAIT_V(8); PG8_WAIT_L(0); PG8_BAR; PG8_MMA(1, 0, At, B0); PG8_MMA(1, 1, At, B1); PG8_BAR; PG8_SCHED;
;             PG8_LDB(B0, 1, 0); PG8_LDB(B1, 1, 1); PG8_SCHED; PG8_LDA(At, 1, 0); PG8_STAGE(PG8_SA(0, 1), a2 + hstepA, voffA);
;             PG8_WAIT_V(8); PG8_WAIT_L(0); PG8_BAR; PG8_MMA(0, 0, At, B0); PG8_MMA(0, 1, At, B1); PG8_BAR; PG8_SCHED;
	v_mfma_f32_16x16x32_bf16 v[60:63], v[96:99], v[160:163], v[60:63]
	v_mfma_f32_16x16x32_bf16 v[56:59], v[108:111], v[160:163], v[56:59]
	v_mfma_f32_16x16x32_bf16 v[44:47], v[96:99], v[182:185], v[44:47]
	v_mfma_f32_16x16x32_bf16 v[40:43], v[108:111], v[182:185], v[40:43]
	v_mfma_f32_16x16x32_bf16 v[28:31], v[96:99], v[194:197], v[28:31]
	v_mfma_f32_16x16x32_bf16 v[24:27], v[108:111], v[194:197], v[24:27]
	v_mfma_f32_16x16x32_bf16 v[12:15], v[96:99], v[208:211], v[12:15]
	v_mfma_f32_16x16x32_bf16 v[8:11], v[108:111], v[208:211], v[8:11]
	v_mfma_f32_16x16x32_bf16 v[60:63], v[100:103], v[164:167], v[60:63]
	v_mfma_f32_16x16x32_bf16 v[56:59], v[116:119], v[164:167], v[56:59]
	v_mfma_f32_16x16x32_bf16 v[44:47], v[100:103], v[186:189], v[44:47]
	v_mfma_f32_16x16x32_bf16 v[40:43], v[116:119], v[186:189], v[40:43]
	v_mfma_f32_16x16x32_bf16 v[28:31], v[100:103], v[204:207], v[28:31]
	v_mfma_f32_16x16x32_bf16 v[24:27], v[116:119], v[204:207], v[24:27]
	v_mfma_f32_16x16x32_bf16 v[12:15], v[100:103], v[212:215], v[12:15]
	v_mfma_f32_16x16x32_bf16 v[8:11], v[116:119], v[212:215], v[8:11]
	v_mfma_f32_16x16x32_bf16 v[52:55], v[144:147], v[160:163], v[52:55]
	v_mfma_f32_16x16x32_bf16 v[48:51], v[152:155], v[160:163], v[48:51]
	v_mfma_f32_16x16x32_bf16 v[36:39], v[144:147], v[182:185], v[36:39]
	v_mfma_f32_16x16x32_bf16 v[32:35], v[152:155], v[182:185], v[32:35]
	v_mfma_f32_16x16x32_bf16 v[20:23], v[144:147], v[194:197], v[20:23]
	v_mfma_f32_16x16x32_bf16 v[16:19], v[152:155], v[194:197], v[16:19]
	v_mfma_f32_16x16x32_bf16 v[4:7], v[144:147], v[208:211], v[4:7]
	v_mfma_f32_16x16x32_bf16 v[0:3], v[152:155], v[208:211], v[0:3]
	v_mfma_f32_16x16x32_bf16 v[52:55], v[148:151], v[164:167], v[52:55]
	v_mfma_f32_16x16x32_bf16 v[48:51], v[156:159], v[164:167], v[48:51]
	v_mfma_f32_16x16x32_bf16 v[36:39], v[148:151], v[186:189], v[36:39]
	v_mfma_f32_16x16x32_bf16 v[32:35], v[156:159], v[186:189], v[32:35]
	v_mfma_f32_16x16x32_bf16 v[20:23], v[148:151], v[204:207], v[20:23]
	v_mfma_f32_16x16x32_bf16 v[16:19], v[156:159], v[204:207], v[16:19]
	v_mfma_f32_16x16x32_bf16 v[4:7], v[148:151], v[212:215], v[4:7]
	v_mfma_f32_16x16x32_bf16 v[0:3], v[156:159], v[212:215], v[0:3]
	s_barrier
	s_setprio 0
	s_add_i32 s86, 0, 0x18000
	s_add_i32 s87, 0, 0x1c000
	v_add_u32_e32 v116, s86, v198
	v_add_u32_e32 v156, s87, v198
	ds_read_b128 v[96:99], v116
	ds_read_b128 v[100:103], v116 offset:1024
	ds_read_b128 v[108:111], v116 offset:2048
	ds_read_b128 v[116:119], v116 offset:3072
	ds_read_b128 v[144:147], v156
	ds_read_b128 v[148:151], v156 offset:1024
	ds_read_b128 v[152:155], v156 offset:2048
	ds_read_b128 v[156:159], v156 offset:3072
	s_add_u32 s46, s46, 0x160000
	s_addc_u32 s47, s47, 0
	s_mov_b32 m0, s50
	v_lshl_add_u64 v[222:223], s[46:47], 0, v[168:169]
	ds_read_b128 v[160:163], v203 offset:32768
	ds_read_b128 v[164:167], v203 offset:33792
	ds_read_b128 v[182:185], v203 offset:34816
	ds_read_b128 v[186:189], v203 offset:35840
	ds_read_b128 v[194:197], v203 offset:36864
	ds_read_b128 v[204:207], v203 offset:37888
	ds_read_b128 v[208:211], v203 offset:38912
	ds_read_b128 v[212:215], v203 offset:39936
	global_load_lds_dwordx4 v[222:223], off
	s_mov_b32 m0, s51
	v_lshl_add_u64 v[222:223], s[46:47], 0, v[172:173]
	global_load_lds_dwordx4 v[222:223], off
	s_waitcnt vmcnt(8)
	s_waitcnt lgkmcnt(0)
	s_setprio 1
	s_barrier
	v_mfma_f32_16x16x32_bf16 v[140:143], v[96:99], v[160:163], v[140:143]
	v_mfma_f32_16x16x32_bf16 v[136:139], v[108:111], v[160:163], v[136:139]
	v_mfma_f32_16x16x32_bf16 v[124:127], v[96:99], v[182:185], v[124:127]
	v_mfma_f32_16x16x32_bf16 v[120:123], v[108:111], v[182:185], v[120:123]
	v_mfma_f32_16x16x32_bf16 v[92:95], v[96:99], v[194:197], v[92:95]
	v_mfma_f32_16x16x32_bf16 v[88:91], v[108:111], v[194:197], v[88:91]
	v_mfma_f32_16x16x32_bf16 v[76:79], v[96:99], v[208:211], v[76:79]
	v_mfma_f32_16x16x32_bf16 v[72:75], v[108:111], v[208:211], v[72:75]
	v_mfma_f32_16x16x32_bf16 v[140:143], v[100:103], v[164:167], v[140:143]
	v_mfma_f32_16x16x32_bf16 v[136:139], v[116:119], v[164:167], v[136:139]
	v_mfma_f32_16x16x32_bf16 v[124:127], v[100:103], v[186:189], v[124:127]
	v_mfma_f32_16x16x32_bf16 v[120:123], v[116:119], v[186:189], v[120:123]
	v_mfma_f32_16x16x32_bf16 v[92:95], v[100:103], v[204:207], v[92:95]
	v_mfma_f32_16x16x32_bf16 v[88:91], v[116:119], v[204:207], v[88:91]
	v_mfma_f32_16x16x32_bf16 v[76:79], v[100:103], v[212:215], v[76:79]
	v_mfma_f32_16x16x32_bf16 v[72:75], v[116:119], v[212:215], v[72:75]
	v_mfma_f32_16x16x32_bf16 v[132:135], v[144:147], v[160:163], v[132:135]
	v_mfma_f32_16x16x32_bf16 v[128:131], v[152:155], v[160:163], v[128:131]
	v_mfma_f32_16x16x32_bf16 v[112:115], v[144:147], v[182:185], v[112:115]
	v_mfma_f32_16x16x32_bf16 v[104:107], v[152:155], v[182:185], v[104:107]
	v_mfma_f32_16x16x32_bf16 v[84:87], v[144:147], v[194:197], v[84:87]
	v_mfma_f32_16x16x32_bf16 v[80:83], v[152:155], v[194:197], v[80:83]
	v_mfma_f32_16x16x32_bf16 v[68:71], v[144:147], v[208:211], v[68:71]
	v_mfma_f32_16x16x32_bf16 v[64:67], v[152:155], v[208:211], v[64:67]
	v_mfma_f32_16x16x32_bf16 v[132:135], v[148:151], v[164:167], v[132:135]
	v_mfma_f32_16x16x32_bf16 v[128:131], v[156:159], v[164:167], v[128:131]
	v_mfma_f32_16x16x32_bf16 v[112:115], v[148:151], v[186:189], v[112:115]
	v_mfma_f32_16x16x32_bf16 v[104:107], v[156:159], v[186:189], v[104:107]
	v_mfma_f32_16x16x32_bf16 v[84:87], v[148:151], v[204:207], v[84:87]
	v_mfma_f32_16x16x32_bf16 v[80:83], v[156:159], v[204:207], v[80:83]
	v_mfma_f32_16x16x32_bf16 v[68:71], v[148:151], v[212:215], v[68:71]
	v_mfma_f32_16x16x32_bf16 v[64:67], v[156:159], v[212:215], v[64:67]
	s_barrier
; #define PG8_STAGE(bufoff, gbase, voff) do { _Pragma("unroll") for (int _i = 0; _i < 2; ++_i) \
;         __builtin_amdgcn_global_load_lds((const unsigned*)((const char*)(gbase) + (voff)[_i]), (LAS unsigned*)(lds + (bufoff) + ldsw + _i * 8192), 16, 0, 0); } while (0)
; #define PG8_LDA(dst, b, h) do { _Pragma("unroll") for (int m = 0; m < 4; ++m) _Pragma("unroll") for (int k = 0; k < 2; ++k) dst[m][k] = *(const LAS bf16x8*)(lds + PG8_SA(b, h) + aoff + m * 2048 + k * 1024); } while (0)
; #define PG8_MMA(ai, bj, At, Bt) do { __builtin_amdgcn_s_setprio(1); _Pragma("unroll") for (int m = 0; m < 4; ++m) _Pragma("unroll") for (int n = 0; n < 2; ++n) _Pragma("unroll") for (int k = 0; k < 2; ++k) \
;         acc[ai][bj][m][n] = __builtin_amdgcn_mfma_f32_16x16x32_bf16(Bt[n][k], At[m][k], acc[ai][bj][m][n], 0, 0, 0); __builtin_amdgcn_s_setprio(0); } while (0)
; #define PG8_WAIT_V(n) asm volatile("s_waitcnt vmcnt(" #n ")" ::: "memory")
; #define PG8_WAIT_L(n) asm volatile("s_waitcnt lgkmcnt(" #n ")" ::: "memory")
; #define PG8_BAR __builtin_amdgcn_s_barrier()
; #define PG8_SCHED __builtin_amdgcn_sched_barrier(0)
; template <class Epi, class Sched = StaticOrder, class EpiSub = NoSub, bool FAST = false>
; __device__ __forceinline__ void gemm_phase(LAS unsigned char* lds, const Gemm g, const Sched& S, const Epi& E, const EpiSub& ES = EpiSub()) {
;     ...
;             PG8_LDA(At, 1, 1); PG8_STAGE(PG8_SB(1, 0), b3, voffB); PG8_STAGE(PG8_SB(1, 1), b3 + hstepB, voffB); PG8_STAGE(PG8_SA(1, 0), a3, voffA);
;             PG8_WAIT_V(8); PG8_WAIT_L(0); PG8_BAR; PG8_MMA(1, 0, At, B0); PG8_MMA(1, 1, At, B1); PG8_BAR; PG8_SCHED;
;     ...
;         if constexpr (FAST && PG8_ALIGN) { if (wr == 0) PG8_BAR; }
	s_setprio 0
	s_add_i32 s46, s86, s27
	v_lshl_add_u64 v[190:191], v[190:191], 0, s[16:17]
	s_mov_b32 m0, s46
	ds_read_b128 v[160:163], v203 offset:49152
	ds_read_b128 v[164:167], v203 offset:50176
	ds_read_b128 v[182:185], v203 offset:51200
	ds_read_b128 v[186:189], v203 offset:52224
	ds_read_b128 v[194:197], v203 offset:53248
	ds_read_b128 v[204:207], v203 offset:54272
	ds_read_b128 v[208:211], v203 offset:55296
	ds_read_b128 v[212:215], v203 offset:56320
	global_load_lds_dwordx4 v[190:191], off
	s_add_i32 m0, s46, 0x2000
	s_add_u32 s44, s44, 0x160080
	v_lshl_add_u64 v[190:191], v[216:217], 0, s[16:17]
	s_addc_u32 s45, s45, 0
	s_add_i32 s46, s87, s27
	global_load_lds_dwordx4 v[190:191], off
	s_mov_b32 m0, s46
	v_lshl_add_u64 v[190:191], s[44:45], 0, v[170:171]
	global_load_lds_dwordx4 v[190:191], off
	s_add_i32 m0, s46, 0x2000
	v_lshl_add_u64 v[190:191], s[44:45], 0, v[174:175]
	global_load_lds_dwordx4 v[190:191], off
	s_mov_b32 m0, s53
	v_lshl_add_u64 v[190:191], v[218:219], 0, s[16:17]
	global_load_lds_dwordx4 v[190:191], off
	s_mov_b32 m0, s54
	v_lshl_add_u64 v[190:191], v[220:221], 0, s[16:17]
	global_load_lds_dwordx4 v[190:191], off
	s_waitcnt vmcnt(8)
	s_waitcnt lgkmcnt(0)
	s_setprio 1
	s_barrier
	v_mfma_f32_16x16x32_bf16 v[60:63], v[96:99], v[160:163], v[60:63]
	v_mfma_f32_16x16x32_bf16 v[56:59], v[108:111], v[160:163], v[56:59]
	v_mfma_f32_16x16x32_bf16 v[44:47], v[96:99], v[182:185], v[44:47]
	v_mfma_f32_16x16x32_bf16 v[40:43], v[108:111], v[182:185], v[40:43]
	v_mfma_f32_16x16x32_bf16 v[28:31], v[96:99], v[194:197], v[28:31]
	v_mfma_f32_16x16x32_bf16 v[24:27], v[108:111], v[194:197], v[24:27]
	v_mfma_f32_16x16x32_bf16 v[12:15], v[96:99], v[208:211], v[12:15]
	v_mfma_f32_16x16x32_bf16 v[8:11], v[108:111], v[208:211], v[8:11]
	v_mfma_f32_16x16x32_bf16 v[60:63], v[100:103], v[164:167], v[60:63]
	v_mfma_f32_16x16x32_bf16 v[56:59], v[116:119], v[164:167], v[56:59]
	v_mfma_f32_16x16x32_bf16 v[44:47], v[100:103], v[186:189], v[44:47]
	v_mfma_f32_16x16x32_bf16 v[40:43], v[116:119], v[186:189], v[40:43]
	v_mfma_f32_16x16x32_bf16 v[28:31], v[100:103], v[204:207], v[28:31]
	v_mfma_f32_16x16x32_bf16 v[24:27], v[116:119], v[204:207], v[24:27]
	v_mfma_f32_16x16x32_bf16 v[12:15], v[100:103], v[212:215], v[12:15]
	v_mfma_f32_16x16x32_bf16 v[8:11], v[116:119], v[212:215], v[8:11]
	v_mfma_f32_16x16x32_bf16 v[52:55], v[144:147], v[160:163], v[52:55]
	v_mfma_f32_16x16x32_bf16 v[48:51], v[152:155], v[160:163], v[48:51]
	v_mfma_f32_16x16x32_bf16 v[36:39], v[144:147], v[182:185], v[36:39]
	v_mfma_f32_16x16x32_bf16 v[32:35], v[152:155], v[182:185], v[32:35]
	v_mfma_f32_16x16x32_bf16 v[20:23], v[144:147], v[194:197], v[20:23]
	v_mfma_f32_16x16x32_bf16 v[16:19], v[152:155], v[194:197], v[16:19]
	v_mfma_f32_16x16x32_bf16 v[4:7], v[144:147], v[208:211], v[4:7]
	v_mfma_f32_16x16x32_bf16 v[0:3], v[152:155], v[208:211], v[0:3]
	v_mfma_f32_16x16x32_bf16 v[52:55], v[148:151], v[164:167], v[52:55]
	v_mfma_f32_16x16x32_bf16 v[48:51], v[156:159], v[164:167], v[48:51]
	v_mfma_f32_16x16x32_bf16 v[36:39], v[148:151], v[186:189], v[36:39]
	v_mfma_f32_16x16x32_bf16 v[32:35], v[156:159], v[186:189], v[32:35]
	v_mfma_f32_16x16x32_bf16 v[20:23], v[148:151], v[204:207], v[20:23]
	v_mfma_f32_16x16x32_bf16 v[16:19], v[156:159], v[204:207], v[16:19]
	v_mfma_f32_16x16x32_bf16 v[4:7], v[148:151], v[212:215], v[4:7]
	v_mfma_f32_16x16x32_bf16 v[0:3], v[156:159], v[212:215], v[0:3]
	s_barrier
	s_setprio 0
	s_add_u32 s42, s42, 0x100
	s_addc_u32 s43, s43, 0
	s_add_u32 s83, s83, 0x100
	s_addc_u32 s84, s84, 0
	s_cmp_ge_u32 s85, s70
	s_mov_b32 s46, s85
	s_cbranch_scc0 .LBB0_1079
	s_and_b64 vcc, exec, s[18:19]
	s_cbranch_vccz .LBB0_1082
	s_barrier
